# all MFMA blocks of the 5 GEMM K-loops 8-byte aligned (s_nop 0 in load segments)
# baseline (speedup 1.0000x reference)
; #define PG8_STAGE(bufoff, gbase, voff) do { _Pragma("unroll") for (int _i = 0; _i < 2; ++_i) \
;         __builtin_amdgcn_global_load_lds((const __attribute__((address_space(1))) unsigned*)((const char*)(gbase) + (voff)[_i]), (LAS unsigned*)(lds + (bufoff) + ldsw + _i * 8192), 16, 0, 0); } while (0)
; #define PG8_LDA(dst, b, h) do { _Pragma("unroll") for (int m = 0; m < 4; ++m) _Pragma("unroll") for (int k = 0; k < 2; ++k) dst[m][k] = *(const LAS bf16x8*)(lds + PG8_SA(b, h) + aoff + m * 2048 + k * 1024); } while (0)
; #define PG8_LDB(dst, b, h) do { _Pragma("unroll") for (int n = 0; n < 2; ++n) _Pragma("unroll") for (int k = 0; k < 2; ++k) dst[n][k] = *(const LAS bf16x8*)(lds + PG8_SB(b, h) + boff + n * 2048 + k * 1024); } while (0)
; #define PG8_MMA(ai, bj, At, Bt) do { __builtin_amdgcn_s_setprio(1); _Pragma("unroll") for (int m = 0; m < 4; ++m) _Pragma("unroll") for (int n = 0; n < 2; ++n) _Pragma("unroll") for (int k = 0; k < 2; ++k) \
;         acc[ai][bj][m][n] = __builtin_amdgcn_mfma_f32_16x16x32_bf16(Bt[n][k], At[m][k], acc[ai][bj][m][n], 0, 0, 0); __builtin_amdgcn_s_setprio(0); } while (0)
; #define PG8_WAIT_V(n) asm volatile("s_waitcnt vmcnt(" #n ")" ::: "memory")
; #define PG8_WAIT_L(n) asm volatile("s_waitcnt lgkmcnt(" #n ")" ::: "memory")
; template <class Epi, class SchedT, bool ALIGN_EPI, bool SP2>
; __device__ __forceinline__ void gemm_phase(LAS unsigned char* lds, const int ldk, const int nt, const SchedT& S, const Epi& E) {
;     ...
;         for (int t = 0; t < nt; t += 2) {
;             const bool last = (t == nt - 2);
;             const char* a1 = cA + (size_t)(t + 1) * kstep;
;             const char* a2 = last ? nA : cA + (size_t)(t + 2) * kstep; const char* b2 = last ? nB : cB + (size_t)(t + 2) * kstep;
;             const char* a3 = a2 + kstep; const char* b3 = b2 + kstep;
;             if constexpr (SP2) {
;             PG8_LDB(B0, 0, 0); PG8_LDB(B1, 0, 1); PG8_SCHED; PG8_LDA(At, 0, 0); PG8_STAGE(PG8_SA(1, 1), a1 + hstep, voffA);
;             PG8_WAIT_V(8); PG8_WAIT_L(0); PG8_BAR; PG8_MMA(0, 0, At, B0); PG8_MMA(0, 1, At, B1); PG8_BAR; PG8_SCHED;
;             PG8_LDA(At, 0, 1); PG8_STAGE(PG8_SB(0, 0), b2, voffB); PG8_STAGE(PG8_SB(0, 1), b2 + hstepB, voffB); PG8_STAGE(PG8_SA(0, 0), a2, voffA);
;             PG8_WAIT_V(8); PG8_WAIT_L(0); PG8_BAR; PG8_MMA(1, 0, At, B0); PG8_MMA(1, 1, At, B1); PG8_BAR; PG8_SCHED;
.LBB0_123:
	s_add_u32 s12, s0, 0xfff80080
	s_addc_u32 s13, s1, -1
	s_add_i32 s34, 0, 0x10000
	s_cmp_eq_u32 s21, 28
	s_cselect_b32 s17, s61, s13
	s_cselect_b32 s16, s60, s12
	v_add_u32_e32 v0, s34, v212
	s_cselect_b32 s13, s31, s19
	s_cselect_b32 s12, s30, s18
	s_add_i32 s38, 0, 0x14000
	s_waitcnt lgkmcnt(0)
	ds_read_b128 v[132:135], v0
	ds_read_b128 v[136:139], v0 offset:1024
	ds_read_b128 v[140:143], v0 offset:2048
	ds_read_b128 v[144:147], v0 offset:3072
	v_add_u32_e32 v0, s38, v212
	ds_read_b128 v[148:151], v0
	ds_read_b128 v[152:155], v0 offset:1024
	ds_read_b128 v[184:187], v0 offset:2048
	ds_read_b128 v[188:191], v0 offset:3072
	v_lshl_add_u64 v[2:3], v[236:237], 0, s[24:25]
	s_mov_b32 m0, s92
	s_nop 0
	global_load_lds_dwordx4 v[2:3], off
	v_lshl_add_u64 v[2:3], v[238:239], 0, s[24:25]
	s_mov_b32 m0, s93
	s_nop 0
	global_load_lds_dwordx4 v[2:3], off
	v_lshl_add_u64 v[2:3], s[0:1], 0, v[180:181]
	s_add_i32 m0, s88, 0xc000
	ds_read_b128 v[192:195], v216
	ds_read_b128 v[196:199], v216 offset:1024
	ds_read_b128 v[200:203], v216 offset:2048
	ds_read_b128 v[204:207], v216 offset:3072
	ds_read_b128 v[218:221], v216 offset:4096
	ds_read_b128 v[222:225], v216 offset:5120
	ds_read_b128 v[226:229], v216 offset:6144
	ds_read_b128 v[230:233], v216 offset:7168
	global_load_lds_dwordx4 v[2:3], off
	v_lshl_add_u64 v[2:3], s[0:1], 0, v[182:183]
	s_add_i32 m0, s88, 0xe000
	s_nop 0
	global_load_lds_dwordx4 v[2:3], off
	s_waitcnt vmcnt(8)
	s_waitcnt lgkmcnt(0)
	s_barrier
	s_setprio 1
	s_waitcnt lgkmcnt(0)
	v_mfma_f32_16x16x32_bf16 v[128:131], v[132:135], v[192:195], v[128:131]
	v_mfma_f32_16x16x32_bf16 v[124:127], v[140:143], v[192:195], v[124:127]
	v_mfma_f32_16x16x32_bf16 v[112:115], v[132:135], v[200:203], v[112:115]
	v_mfma_f32_16x16x32_bf16 v[108:111], v[140:143], v[200:203], v[108:111]
	v_mfma_f32_16x16x32_bf16 v[96:99], v[132:135], v[218:221], v[96:99]
	v_mfma_f32_16x16x32_bf16 v[92:95], v[140:143], v[218:221], v[92:95]
	v_mfma_f32_16x16x32_bf16 v[80:83], v[132:135], v[226:229], v[80:83]
	v_mfma_f32_16x16x32_bf16 v[76:79], v[140:143], v[226:229], v[76:79]
	v_mfma_f32_16x16x32_bf16 v[128:131], v[136:139], v[196:199], v[128:131]
	v_mfma_f32_16x16x32_bf16 v[124:127], v[144:147], v[196:199], v[124:127]
	v_mfma_f32_16x16x32_bf16 v[112:115], v[136:139], v[204:207], v[112:115]
	v_mfma_f32_16x16x32_bf16 v[108:111], v[144:147], v[204:207], v[108:111]
	v_mfma_f32_16x16x32_bf16 v[96:99], v[136:139], v[222:225], v[96:99]
	v_mfma_f32_16x16x32_bf16 v[92:95], v[144:147], v[222:225], v[92:95]
	v_mfma_f32_16x16x32_bf16 v[80:83], v[136:139], v[230:233], v[80:83]
	v_mfma_f32_16x16x32_bf16 v[76:79], v[144:147], v[230:233], v[76:79]
	s_setprio 0
	s_setprio 1
	v_mfma_f32_16x16x32_bf16 v[120:123], v[148:151], v[192:195], v[120:123]
	v_mfma_f32_16x16x32_bf16 v[116:119], v[184:187], v[192:195], v[116:119]
	v_mfma_f32_16x16x32_bf16 v[104:107], v[148:151], v[200:203], v[104:107]
	v_mfma_f32_16x16x32_bf16 v[100:103], v[184:187], v[200:203], v[100:103]
	v_mfma_f32_16x16x32_bf16 v[88:91], v[148:151], v[218:221], v[88:91]
	v_mfma_f32_16x16x32_bf16 v[84:87], v[184:187], v[218:221], v[84:87]
	v_mfma_f32_16x16x32_bf16 v[72:75], v[148:151], v[226:229], v[72:75]
	v_mfma_f32_16x16x32_bf16 v[68:71], v[184:187], v[226:229], v[68:71]
	v_mfma_f32_16x16x32_bf16 v[120:123], v[152:155], v[196:199], v[120:123]
	v_mfma_f32_16x16x32_bf16 v[116:119], v[188:191], v[196:199], v[116:119]
	v_mfma_f32_16x16x32_bf16 v[104:107], v[152:155], v[204:207], v[104:107]
	v_mfma_f32_16x16x32_bf16 v[100:103], v[188:191], v[204:207], v[100:103]
	v_mfma_f32_16x16x32_bf16 v[88:91], v[152:155], v[222:225], v[88:91]
	v_mfma_f32_16x16x32_bf16 v[84:87], v[188:191], v[222:225], v[84:87]
	v_mfma_f32_16x16x32_bf16 v[72:75], v[152:155], v[230:233], v[72:75]
	v_mfma_f32_16x16x32_bf16 v[68:71], v[188:191], v[230:233], v[68:71]
	s_setprio 0
	s_barrier
	s_add_i32 s34, s34, s87
	v_lshl_add_u64 v[208:209], s[12:13], 0, v[158:159]
	s_mov_b32 m0, s34
	ds_read_b128 v[192:195], v216 offset:16384
	ds_read_b128 v[196:199], v216 offset:17408
	ds_read_b128 v[200:203], v216 offset:18432
	ds_read_b128 v[204:207], v216 offset:19456
	ds_read_b128 v[218:221], v216 offset:20480
	ds_read_b128 v[222:225], v216 offset:21504
	ds_read_b128 v[226:229], v216 offset:22528
	ds_read_b128 v[230:233], v216 offset:23552
	global_load_lds_dwordx4 v[208:209], off
	s_add_i32 m0, s34, 0x2000
	s_add_u32 s34, s12, 0x20000
	v_lshl_add_u64 v[234:235], s[12:13], 0, v[174:175]
	s_addc_u32 s35, s13, 0
	s_add_i32 s38, s38, s87
	global_load_lds_dwordx4 v[234:235], off
	v_lshl_add_u64 v[2:3], s[34:35], 0, v[158:159]
	s_mov_b32 m0, s38
	v_lshl_add_u64 v[236:237], s[16:17], 0, v[156:157]
	global_load_lds_dwordx4 v[2:3], off
	v_lshl_add_u64 v[2:3], s[34:35], 0, v[174:175]
	s_add_i32 m0, s38, 0x2000
	v_lshl_add_u64 v[238:239], s[16:17], 0, v[160:161]
	global_load_lds_dwordx4 v[2:3], off
	s_waitcnt vmcnt(6)
	s_waitcnt lgkmcnt(0)
	s_barrier
; #define PG8_STAGE(bufoff, gbase, voff) do { _Pragma("unroll") for (int _i = 0; _i < 2; ++_i) \
;         __builtin_amdgcn_global_load_lds((const __attribute__((address_space(1))) unsigned*)((const char*)(gbase) + (voff)[_i]), (LAS unsigned*)(lds + (bufoff) + ldsw + _i * 8192), 16, 0, 0); } while (0)
; #define PG8_LDA(dst, b, h) do { _Pragma("unroll") for (int m = 0; m < 4; ++m) _Pragma("unroll") for (int k = 0; k < 2; ++k) dst[m][k] = *(const LAS bf16x8*)(lds + PG8_SA(b, h) + aoff + m * 2048 + k * 1024); } while (0)
; #define PG8_LDB(dst, b, h) do { _Pragma("unroll") for (int n = 0; n < 2; ++n) _Pragma("unroll") for (int k = 0; k < 2; ++k) dst[n][k] = *(const LAS bf16x8*)(lds + PG8_SB(b, h) + boff + n * 2048 + k * 1024); } while (0)
; #define PG8_MMA(ai, bj, At, Bt) do { __builtin_amdgcn_s_setprio(1); _Pragma("unroll") for (int m = 0; m < 4; ++m) _Pragma("unroll") for (int n = 0; n < 2; ++n) _Pragma("unroll") for (int k = 0; k < 2; ++k) \
;         acc[ai][bj][m][n] = __builtin_amdgcn_mfma_f32_16x16x32_bf16(Bt[n][k], At[m][k], acc[ai][bj][m][n], 0, 0, 0); __builtin_amdgcn_s_setprio(0); } while (0)
; #define PG8_WAIT_V(n) asm volatile("s_waitcnt vmcnt(" #n ")" ::: "memory")
; #define PG8_WAIT_L(n) asm volatile("s_waitcnt lgkmcnt(" #n ")" ::: "memory")
; #define PG8_BAR __builtin_amdgcn_s_barrier()
; #define PG8_SCHED __builtin_amdgcn_sched_barrier(0)
; template <class Epi, class SchedT, bool ALIGN_EPI, bool SP2>
; __device__ __forceinline__ void gemm_phase(LAS unsigned char* lds, const int ldk, const int nt, const SchedT& S, const Epi& E) {
;     ...
;             PG8_WAIT_V(8); PG8_WAIT_L(0); PG8_BAR; PG8_MMA(1, 0, At, B0); PG8_MMA(1, 1, At, B1); PG8_BAR; PG8_SCHED;
;             PG8_LDB(B0, 1, 0); PG8_LDB(B1, 1, 1); PG8_SCHED; PG8_LDA(At, 1, 0); PG8_STAGE(PG8_SA(0, 1), a2 + hstep, voffA);
;             PG8_WAIT_V(8); PG8_WAIT_L(0); PG8_BAR; PG8_MMA(0, 0, At, B0); PG8_MMA(0, 1, At, B1); PG8_BAR; PG8_SCHED;
	s_setprio 1
	s_waitcnt lgkmcnt(0)
	v_mfma_f32_16x16x32_bf16 v[64:67], v[132:135], v[192:195], v[64:67]
	v_mfma_f32_16x16x32_bf16 v[60:63], v[140:143], v[192:195], v[60:63]
	v_mfma_f32_16x16x32_bf16 v[48:51], v[132:135], v[200:203], v[48:51]
	v_mfma_f32_16x16x32_bf16 v[44:47], v[140:143], v[200:203], v[44:47]
	v_mfma_f32_16x16x32_bf16 v[32:35], v[132:135], v[218:221], v[32:35]
	v_mfma_f32_16x16x32_bf16 v[28:31], v[140:143], v[218:221], v[28:31]
	v_mfma_f32_16x16x32_bf16 v[16:19], v[132:135], v[226:229], v[16:19]
	v_mfma_f32_16x16x32_bf16 v[12:15], v[140:143], v[226:229], v[12:15]
	v_mfma_f32_16x16x32_bf16 v[64:67], v[136:139], v[196:199], v[64:67]
	v_mfma_f32_16x16x32_bf16 v[60:63], v[144:147], v[196:199], v[60:63]
	v_mfma_f32_16x16x32_bf16 v[48:51], v[136:139], v[204:207], v[48:51]
	v_mfma_f32_16x16x32_bf16 v[44:47], v[144:147], v[204:207], v[44:47]
	v_mfma_f32_16x16x32_bf16 v[32:35], v[136:139], v[222:225], v[32:35]
	v_mfma_f32_16x16x32_bf16 v[28:31], v[144:147], v[222:225], v[28:31]
	v_mfma_f32_16x16x32_bf16 v[16:19], v[136:139], v[230:233], v[16:19]
	v_mfma_f32_16x16x32_bf16 v[12:15], v[144:147], v[230:233], v[12:15]
	s_setprio 0
	s_setprio 1
	v_mfma_f32_16x16x32_bf16 v[56:59], v[148:151], v[192:195], v[56:59]
	v_mfma_f32_16x16x32_bf16 v[52:55], v[184:187], v[192:195], v[52:55]
	v_mfma_f32_16x16x32_bf16 v[40:43], v[148:151], v[200:203], v[40:43]
	v_mfma_f32_16x16x32_bf16 v[36:39], v[184:187], v[200:203], v[36:39]
	v_mfma_f32_16x16x32_bf16 v[24:27], v[148:151], v[218:221], v[24:27]
	v_mfma_f32_16x16x32_bf16 v[20:23], v[184:187], v[218:221], v[20:23]
	v_mfma_f32_16x16x32_bf16 v[8:11], v[148:151], v[226:229], v[8:11]
	v_mfma_f32_16x16x32_bf16 v[2:5], v[184:187], v[226:229], v[4:7]
	v_mfma_f32_16x16x32_bf16 v[56:59], v[152:155], v[196:199], v[56:59]
	v_mfma_f32_16x16x32_bf16 v[52:55], v[188:191], v[196:199], v[52:55]
	v_mfma_f32_16x16x32_bf16 v[40:43], v[152:155], v[204:207], v[40:43]
	v_mfma_f32_16x16x32_bf16 v[36:39], v[188:191], v[204:207], v[36:39]
	v_mfma_f32_16x16x32_bf16 v[24:27], v[152:155], v[222:225], v[24:27]
	v_mfma_f32_16x16x32_bf16 v[20:23], v[188:191], v[222:225], v[20:23]
	v_mfma_f32_16x16x32_bf16 v[8:11], v[152:155], v[230:233], v[8:11]
	v_mfma_f32_16x16x32_bf16 v[2:5], v[188:191], v[230:233], v[2:5]
	s_setprio 0
	s_barrier
	s_add_i32 s34, 0, 0x18000
	v_add_u32_e32 v0, s34, v212
	s_add_i32 s35, 0, 0x1c000
	ds_read_b128 v[132:135], v0
	ds_read_b128 v[136:139], v0 offset:1024
	ds_read_b128 v[140:143], v0 offset:2048
	ds_read_b128 v[144:147], v0 offset:3072
	v_add_u32_e32 v0, s35, v212
	ds_read_b128 v[148:151], v0
	ds_read_b128 v[152:155], v0 offset:1024
	ds_read_b128 v[184:187], v0 offset:2048
	ds_read_b128 v[188:191], v0 offset:3072
	s_add_u32 s16, s16, 0x80000
	s_addc_u32 s17, s17, 0
	s_mov_b32 m0, s88
	s_nop 0
	global_load_lds_dwordx4 v[236:237], off
	s_mov_b32 m0, s89
	s_nop 0
	global_load_lds_dwordx4 v[238:239], off
	s_mov_b32 m0, s90
	v_lshl_add_u64 v[6:7], s[16:17], 0, v[156:157]
	ds_read_b128 v[192:195], v216 offset:32768
	ds_read_b128 v[196:199], v216 offset:33792
	ds_read_b128 v[200:203], v216 offset:34816
	ds_read_b128 v[204:207], v216 offset:35840
	ds_read_b128 v[218:221], v216 offset:36864
	ds_read_b128 v[222:225], v216 offset:37888
	ds_read_b128 v[226:229], v216 offset:38912
	ds_read_b128 v[230:233], v216 offset:39936
	global_load_lds_dwordx4 v[6:7], off
	v_lshl_add_u64 v[6:7], s[16:17], 0, v[160:161]
	s_mov_b32 m0, s91
	s_nop 0
	global_load_lds_dwordx4 v[6:7], off
	s_nop 0
	s_waitcnt vmcnt(8)
	s_waitcnt lgkmcnt(0)
	s_barrier
; #define PG8_STAGE(bufoff, gbase, voff) do { _Pragma("unroll") for (int _i = 0; _i < 2; ++_i) \
;         __builtin_amdgcn_global_load_lds((const __attribute__((address_space(1))) unsigned*)((const char*)(gbase) + (voff)[_i]), (LAS unsigned*)(lds + (bufoff) + ldsw + _i * 8192), 16, 0, 0); } while (0)
; #define PG8_LDA(dst, b, h) do { _Pragma("unroll") for (int m = 0; m < 4; ++m) _Pragma("unroll") for (int k = 0; k < 2; ++k) dst[m][k] = *(const LAS bf16x8*)(lds + PG8_SA(b, h) + aoff + m * 2048 + k * 1024); } while (0)
; #define PG8_MMA(ai, bj, At, Bt) do { __builtin_amdgcn_s_setprio(1); _Pragma("unroll") for (int m = 0; m < 4; ++m) _Pragma("unroll") for (int n = 0; n < 2; ++n) _Pragma("unroll") for (int k = 0; k < 2; ++k) \
;         acc[ai][bj][m][n] = __builtin_amdgcn_mfma_f32_16x16x32_bf16(Bt[n][k], At[m][k], acc[ai][bj][m][n], 0, 0, 0); __builtin_amdgcn_s_setprio(0); } while (0)
; #define PG8_WAIT_V(n) asm volatile("s_waitcnt vmcnt(" #n ")" ::: "memory")
; #define PG8_WAIT_L(n) asm volatile("s_waitcnt lgkmcnt(" #n ")" ::: "memory")
; #define PG8_BAR __builtin_amdgcn_s_barrier()
; #define PG8_SCHED __builtin_amdgcn_sched_barrier(0)
; template <class Epi, class SchedT, bool ALIGN_EPI, bool SP2>
; __device__ __forceinline__ void gemm_phase(LAS unsigned char* lds, const int ldk, const int nt, const SchedT& S, const Epi& E) {
;     ...
;             PG8_WAIT_V(8); PG8_WAIT_L(0); PG8_BAR; PG8_MMA(0, 0, At, B0); PG8_MMA(0, 1, At, B1); PG8_BAR; PG8_SCHED;
;             PG8_LDA(At, 1, 1); PG8_STAGE(PG8_SB(1, 0), b3, voffB); PG8_STAGE(PG8_SB(1, 1), b3 + hstepB, voffB); PG8_STAGE(PG8_SA(1, 0), a3, voffA);
;             PG8_WAIT_V(8); PG8_WAIT_L(0); PG8_BAR; PG8_MMA(1, 0, At, B0); PG8_MMA(1, 1, At, B1); PG8_BAR; PG8_SCHED;
;     ...
;         }
;         if constexpr (ALIGN_EPI) { if (wr == 0) PG8_BAR; }
	s_setprio 1
	s_waitcnt lgkmcnt(0)
	v_mfma_f32_16x16x32_bf16 v[128:131], v[132:135], v[192:195], v[128:131]
	v_mfma_f32_16x16x32_bf16 v[124:127], v[140:143], v[192:195], v[124:127]
	v_mfma_f32_16x16x32_bf16 v[112:115], v[132:135], v[200:203], v[112:115]
	v_mfma_f32_16x16x32_bf16 v[108:111], v[140:143], v[200:203], v[108:111]
	v_mfma_f32_16x16x32_bf16 v[96:99], v[132:135], v[218:221], v[96:99]
	v_mfma_f32_16x16x32_bf16 v[92:95], v[140:143], v[218:221], v[92:95]
	v_mfma_f32_16x16x32_bf16 v[80:83], v[132:135], v[226:229], v[80:83]
	v_mfma_f32_16x16x32_bf16 v[76:79], v[140:143], v[226:229], v[76:79]
	v_mfma_f32_16x16x32_bf16 v[128:131], v[136:139], v[196:199], v[128:131]
	v_mfma_f32_16x16x32_bf16 v[124:127], v[144:147], v[196:199], v[124:127]
	v_mfma_f32_16x16x32_bf16 v[112:115], v[136:139], v[204:207], v[112:115]
	v_mfma_f32_16x16x32_bf16 v[108:111], v[144:147], v[204:207], v[108:111]
	v_mfma_f32_16x16x32_bf16 v[96:99], v[136:139], v[222:225], v[96:99]
	v_mfma_f32_16x16x32_bf16 v[92:95], v[144:147], v[222:225], v[92:95]
	v_mfma_f32_16x16x32_bf16 v[80:83], v[136:139], v[230:233], v[80:83]
	v_mfma_f32_16x16x32_bf16 v[76:79], v[144:147], v[230:233], v[76:79]
	s_setprio 0
	s_setprio 1
	v_mfma_f32_16x16x32_bf16 v[120:123], v[148:151], v[192:195], v[120:123]
	v_mfma_f32_16x16x32_bf16 v[116:119], v[184:187], v[192:195], v[116:119]
	v_mfma_f32_16x16x32_bf16 v[104:107], v[148:151], v[200:203], v[104:107]
	v_mfma_f32_16x16x32_bf16 v[100:103], v[184:187], v[200:203], v[100:103]
	v_mfma_f32_16x16x32_bf16 v[88:91], v[148:151], v[218:221], v[88:91]
	v_mfma_f32_16x16x32_bf16 v[84:87], v[184:187], v[218:221], v[84:87]
	v_mfma_f32_16x16x32_bf16 v[72:75], v[148:151], v[226:229], v[72:75]
	v_mfma_f32_16x16x32_bf16 v[68:71], v[184:187], v[226:229], v[68:71]
	v_mfma_f32_16x16x32_bf16 v[120:123], v[152:155], v[196:199], v[120:123]
	v_mfma_f32_16x16x32_bf16 v[116:119], v[188:191], v[196:199], v[116:119]
	v_mfma_f32_16x16x32_bf16 v[104:107], v[152:155], v[204:207], v[104:107]
	v_mfma_f32_16x16x32_bf16 v[100:103], v[188:191], v[204:207], v[100:103]
	v_mfma_f32_16x16x32_bf16 v[88:91], v[152:155], v[222:225], v[88:91]
	v_mfma_f32_16x16x32_bf16 v[84:87], v[188:191], v[222:225], v[84:87]
	v_mfma_f32_16x16x32_bf16 v[72:75], v[152:155], v[230:233], v[72:75]
	v_mfma_f32_16x16x32_bf16 v[68:71], v[188:191], v[230:233], v[68:71]
	s_setprio 0
	s_barrier
	s_add_i32 s16, s34, s87
	v_lshl_add_u64 v[6:7], v[208:209], 0, s[24:25]
	s_mov_b32 m0, s16
	ds_read_b128 v[192:195], v216 offset:49152
	ds_read_b128 v[196:199], v216 offset:50176
	ds_read_b128 v[200:203], v216 offset:51200
	ds_read_b128 v[204:207], v216 offset:52224
	ds_read_b128 v[218:221], v216 offset:53248
	ds_read_b128 v[222:225], v216 offset:54272
	ds_read_b128 v[226:229], v216 offset:55296
	ds_read_b128 v[230:233], v216 offset:56320
	global_load_lds_dwordx4 v[6:7], off
	s_add_i32 m0, s16, 0x2000
	s_add_u32 s12, s12, 0x20080
	v_lshl_add_u64 v[6:7], v[234:235], 0, s[24:25]
	s_addc_u32 s13, s13, 0
	s_add_i32 s16, s35, s87
	global_load_lds_dwordx4 v[6:7], off
	v_lshl_add_u64 v[6:7], s[12:13], 0, v[158:159]
	s_mov_b32 m0, s16
	s_nop 0
	global_load_lds_dwordx4 v[6:7], off
	v_lshl_add_u64 v[6:7], s[12:13], 0, v[174:175]
	s_add_i32 m0, s16, 0x2000
	s_nop 0
	global_load_lds_dwordx4 v[6:7], off
	s_waitcnt vmcnt(6)
	s_waitcnt lgkmcnt(0)
	s_barrier
	s_setprio 1
	s_waitcnt lgkmcnt(0)
	v_mfma_f32_16x16x32_bf16 v[64:67], v[132:135], v[192:195], v[64:67]
	v_mfma_f32_16x16x32_bf16 v[60:63], v[140:143], v[192:195], v[60:63]
	v_mfma_f32_16x16x32_bf16 v[48:51], v[132:135], v[200:203], v[48:51]
	v_mfma_f32_16x16x32_bf16 v[44:47], v[140:143], v[200:203], v[44:47]
	v_mfma_f32_16x16x32_bf16 v[32:35], v[132:135], v[218:221], v[32:35]
	v_mfma_f32_16x16x32_bf16 v[28:31], v[140:143], v[218:221], v[28:31]
	v_mfma_f32_16x16x32_bf16 v[16:19], v[132:135], v[226:229], v[16:19]
	v_mfma_f32_16x16x32_bf16 v[12:15], v[140:143], v[226:229], v[12:15]
	v_mfma_f32_16x16x32_bf16 v[64:67], v[136:139], v[196:199], v[64:67]
	v_mfma_f32_16x16x32_bf16 v[60:63], v[144:147], v[196:199], v[60:63]
	v_mfma_f32_16x16x32_bf16 v[48:51], v[136:139], v[204:207], v[48:51]
	v_mfma_f32_16x16x32_bf16 v[44:47], v[144:147], v[204:207], v[44:47]
	v_mfma_f32_16x16x32_bf16 v[32:35], v[136:139], v[222:225], v[32:35]
	v_mfma_f32_16x16x32_bf16 v[28:31], v[144:147], v[222:225], v[28:31]
	v_mfma_f32_16x16x32_bf16 v[16:19], v[136:139], v[230:233], v[16:19]
	v_mfma_f32_16x16x32_bf16 v[12:15], v[144:147], v[230:233], v[12:15]
	s_setprio 0
	s_setprio 1
	v_mfma_f32_16x16x32_bf16 v[56:59], v[148:151], v[192:195], v[56:59]
	v_mfma_f32_16x16x32_bf16 v[52:55], v[184:187], v[192:195], v[52:55]
	v_mfma_f32_16x16x32_bf16 v[40:43], v[148:151], v[200:203], v[40:43]
	v_mfma_f32_16x16x32_bf16 v[36:39], v[184:187], v[200:203], v[36:39]
	v_mfma_f32_16x16x32_bf16 v[24:27], v[148:151], v[218:221], v[24:27]
	v_mfma_f32_16x16x32_bf16 v[20:23], v[184:187], v[218:221], v[20:23]
	v_mfma_f32_16x16x32_bf16 v[6:9], v[148:151], v[226:229], v[8:11]
	v_mfma_f32_16x16x32_bf16 v[2:5], v[184:187], v[226:229], v[2:5]
	v_mfma_f32_16x16x32_bf16 v[56:59], v[152:155], v[196:199], v[56:59]
	v_mfma_f32_16x16x32_bf16 v[52:55], v[188:191], v[196:199], v[52:55]
	v_mfma_f32_16x16x32_bf16 v[40:43], v[152:155], v[204:207], v[40:43]
	v_mfma_f32_16x16x32_bf16 v[36:39], v[188:191], v[204:207], v[36:39]
	v_mfma_f32_16x16x32_bf16 v[24:27], v[152:155], v[222:225], v[24:27]
	v_mfma_f32_16x16x32_bf16 v[20:23], v[188:191], v[222:225], v[20:23]
	v_mfma_f32_16x16x32_bf16 v[8:11], v[152:155], v[230:233], v[6:9]
	v_mfma_f32_16x16x32_bf16 v[4:7], v[188:191], v[230:233], v[2:5]
	s_setprio 0
	s_barrier
	s_add_i32 s21, s21, 2
	s_add_u32 s0, s0, 0x100
	s_addc_u32 s1, s1, 0
	s_add_u32 s18, s18, 0x100
	s_addc_u32 s19, s19, 0
	s_cmp_gt_u32 s21, 29
	s_cbranch_scc0 .LBB0_123
	s_and_b64 vcc, exec, s[58:59]
	s_cbranch_vccz .LBB0_126
	s_barrier

; #define PG8_STAGE(bufoff, gbase, voff) do { _Pragma("unroll") for (int _i = 0; _i < 2; ++_i) \
;         __builtin_amdgcn_global_load_lds((const __attribute__((address_space(1))) unsigned*)((const char*)(gbase) + (voff)[_i]), (LAS unsigned*)(lds + (bufoff) + ldsw + _i * 8192), 16, 0, 0); } while (0)
; #define PG8_LDA(dst, b, h) do { _Pragma("unroll") for (int m = 0; m < 4; ++m) _Pragma("unroll") for (int k = 0; k < 2; ++k) dst[m][k] = *(const LAS bf16x8*)(lds + PG8_SA(b, h) + aoff + m * 2048 + k * 1024); } while (0)
; #define PG8_LDB(dst, b, h) do { _Pragma("unroll") for (int n = 0; n < 2; ++n) _Pragma("unroll") for (int k = 0; k < 2; ++k) dst[n][k] = *(const LAS bf16x8*)(lds + PG8_SB(b, h) + boff + n * 2048 + k * 1024); } while (0)
; #define PG8_MMA(ai, bj, At, Bt) do { __builtin_amdgcn_s_setprio(1); _Pragma("unroll") for (int m = 0; m < 4; ++m) _Pragma("unroll") for (int n = 0; n < 2; ++n) _Pragma("unroll") for (int k = 0; k < 2; ++k) \
;         acc[ai][bj][m][n] = __builtin_amdgcn_mfma_f32_16x16x32_bf16(Bt[n][k], At[m][k], acc[ai][bj][m][n], 0, 0, 0); __builtin_amdgcn_s_setprio(0); } while (0)
; #define PG8_WAIT_V(n) asm volatile("s_waitcnt vmcnt(" #n ")" ::: "memory")
; #define PG8_WAIT_L(n) asm volatile("s_waitcnt lgkmcnt(" #n ")" ::: "memory")
; #define PG8_BAR __builtin_amdgcn_s_barrier()
; template <class Epi, class SchedT, bool ALIGN_EPI, bool SP2>
; __device__ __forceinline__ void gemm_phase(LAS unsigned char* lds, const int ldk, const int nt, const SchedT& S, const Epi& E) {
;     ...
;             const bool last = (t == nt - 2);
;             const char* a1 = cA + (size_t)(t + 1) * kstep;
;             const char* a2 = last ? nA : cA + (size_t)(t + 2) * kstep; const char* b2 = last ? nB : cB + (size_t)(t + 2) * kstep;
;             const char* a3 = a2 + kstep; const char* b3 = b2 + kstep;
;             if constexpr (SP2) {
;             PG8_LDB(B0, 0, 0); PG8_LDB(B1, 0, 1); PG8_SCHED; PG8_LDA(At, 0, 0); PG8_STAGE(PG8_SA(1, 1), a1 + hstep, voffA);
;             PG8_WAIT_V(8); PG8_WAIT_L(0); PG8_BAR; PG8_MMA(0, 0, At, B0); PG8_MMA(0, 1, At, B1); PG8_BAR; PG8_SCHED;
;             PG8_LDA(At, 0, 1); PG8_STAGE(PG8_SB(0, 0), b2, voffB); PG8_STAGE(PG8_SB(0, 1), b2 + hstepB, voffB); PG8_STAGE(PG8_SA(0, 0), a2, voffA);
;             PG8_WAIT_V(8); PG8_WAIT_L(0); PG8_BAR; PG8_MMA(1, 0, At, B0); PG8_MMA(1, 1, At, B1); PG8_BAR; PG8_SCHED;
.LBB0_534:
	s_add_u32 s36, s34, 0xfff80080
	s_addc_u32 s37, s35, -1
	s_add_i32 s49, 0, 0x10000
	s_cmp_eq_u32 s47, 12
	s_cselect_b32 s41, s1, s37
	s_cselect_b32 s40, s0, s36
	v_add_u32_e32 v0, s49, v159
	s_cselect_b32 s37, s53, s20
	s_cselect_b32 s36, s52, s17
	s_add_i32 s51, 0, 0x14000
	ds_read_b128 v[144:147], v0
	ds_read_b128 v[148:151], v0 offset:1024
	ds_read_b128 v[152:155], v0 offset:2048
	ds_read_b128 v[174:177], v0 offset:3072
	v_add_u32_e32 v0, s51, v159
	ds_read_b128 v[178:181], v0
	ds_read_b128 v[182:185], v0 offset:1024
	ds_read_b128 v[186:189], v0 offset:2048
	ds_read_b128 v[190:193], v0 offset:3072
	v_lshl_add_u64 v[2:3], s[34:35], 0, v[140:141]
	s_add_i32 m0, s57, 0xc000
	ds_read_b128 v[194:197], v161
	ds_read_b128 v[198:201], v161 offset:1024
	ds_read_b128 v[202:205], v161 offset:2048
	ds_read_b128 v[206:209], v161 offset:3072
	ds_read_b128 v[210:213], v161 offset:4096
	ds_read_b128 v[214:217], v161 offset:5120
	ds_read_b128 v[218:221], v161 offset:6144
	ds_read_b128 v[222:225], v161 offset:7168
	global_load_lds_dwordx4 v[2:3], off
	v_lshl_add_u64 v[2:3], s[34:35], 0, v[142:143]
	s_add_i32 m0, s57, 0xe000
	s_nop 0
	global_load_lds_dwordx4 v[2:3], off
	s_nop 0
	s_nop 0
	s_waitcnt vmcnt(8)
	s_waitcnt lgkmcnt(0)
	s_barrier
	s_setprio 1
	s_waitcnt lgkmcnt(0)
	v_mfma_f32_16x16x32_bf16 v[128:131], v[144:147], v[194:197], v[128:131]
	v_mfma_f32_16x16x32_bf16 v[124:127], v[152:155], v[194:197], v[124:127]
	v_mfma_f32_16x16x32_bf16 v[120:123], v[144:147], v[202:205], v[120:123]
	v_mfma_f32_16x16x32_bf16 v[116:119], v[152:155], v[202:205], v[116:119]
	v_mfma_f32_16x16x32_bf16 v[112:115], v[144:147], v[210:213], v[112:115]
	v_mfma_f32_16x16x32_bf16 v[108:111], v[152:155], v[210:213], v[108:111]
	v_mfma_f32_16x16x32_bf16 v[104:107], v[144:147], v[218:221], v[104:107]
	v_mfma_f32_16x16x32_bf16 v[100:103], v[152:155], v[218:221], v[100:103]
	v_mfma_f32_16x16x32_bf16 v[128:131], v[148:151], v[198:201], v[128:131]
	v_mfma_f32_16x16x32_bf16 v[124:127], v[174:177], v[198:201], v[124:127]
	v_mfma_f32_16x16x32_bf16 v[120:123], v[148:151], v[206:209], v[120:123]
	v_mfma_f32_16x16x32_bf16 v[116:119], v[174:177], v[206:209], v[116:119]
	v_mfma_f32_16x16x32_bf16 v[112:115], v[148:151], v[214:217], v[112:115]
	v_mfma_f32_16x16x32_bf16 v[108:111], v[174:177], v[214:217], v[108:111]
	v_mfma_f32_16x16x32_bf16 v[104:107], v[148:151], v[222:225], v[104:107]
	v_mfma_f32_16x16x32_bf16 v[100:103], v[174:177], v[222:225], v[100:103]
	s_setprio 0
	s_setprio 1
	v_mfma_f32_16x16x32_bf16 v[96:99], v[178:181], v[194:197], v[96:99]
	v_mfma_f32_16x16x32_bf16 v[92:95], v[186:189], v[194:197], v[92:95]
	v_mfma_f32_16x16x32_bf16 v[88:91], v[178:181], v[202:205], v[88:91]
	v_mfma_f32_16x16x32_bf16 v[84:87], v[186:189], v[202:205], v[84:87]
	v_mfma_f32_16x16x32_bf16 v[80:83], v[178:181], v[210:213], v[80:83]
	v_mfma_f32_16x16x32_bf16 v[76:79], v[186:189], v[210:213], v[76:79]
	v_mfma_f32_16x16x32_bf16 v[72:75], v[178:181], v[218:221], v[72:75]
	v_mfma_f32_16x16x32_bf16 v[68:71], v[186:189], v[218:221], v[68:71]
	v_mfma_f32_16x16x32_bf16 v[96:99], v[182:185], v[198:201], v[96:99]
	v_mfma_f32_16x16x32_bf16 v[92:95], v[190:193], v[198:201], v[92:95]
	v_mfma_f32_16x16x32_bf16 v[88:91], v[182:185], v[206:209], v[88:91]
	v_mfma_f32_16x16x32_bf16 v[84:87], v[190:193], v[206:209], v[84:87]
	v_mfma_f32_16x16x32_bf16 v[80:83], v[182:185], v[214:217], v[80:83]
	v_mfma_f32_16x16x32_bf16 v[76:79], v[190:193], v[214:217], v[76:79]
	v_mfma_f32_16x16x32_bf16 v[72:75], v[182:185], v[222:225], v[72:75]
	v_mfma_f32_16x16x32_bf16 v[68:71], v[190:193], v[222:225], v[68:71]
	s_setprio 0
	s_barrier
	s_add_i32 s49, s49, s56
	v_lshl_add_u64 v[156:157], s[36:37], 0, v[134:135]
	s_mov_b32 m0, s49
	ds_read_b128 v[194:197], v161 offset:16384
	ds_read_b128 v[198:201], v161 offset:17408
	ds_read_b128 v[202:205], v161 offset:18432
	ds_read_b128 v[206:209], v161 offset:19456
	ds_read_b128 v[210:213], v161 offset:20480
	ds_read_b128 v[214:217], v161 offset:21504
	ds_read_b128 v[218:221], v161 offset:22528
	ds_read_b128 v[222:225], v161 offset:23552
	global_load_lds_dwordx4 v[156:157], off
	s_add_i32 m0, s49, 0x2000
	s_add_u32 s82, s36, 0x20000
	v_lshl_add_u64 v[226:227], s[36:37], 0, v[138:139]
	s_addc_u32 s83, s37, 0
	s_add_i32 s49, s51, s56
	global_load_lds_dwordx4 v[226:227], off
	v_lshl_add_u64 v[2:3], s[82:83], 0, v[134:135]
	s_mov_b32 m0, s49
	v_lshl_add_u64 v[228:229], s[40:41], 0, v[132:133]
	global_load_lds_dwordx4 v[2:3], off
	v_lshl_add_u64 v[2:3], s[82:83], 0, v[138:139]
	s_add_i32 m0, s49, 0x2000
	v_lshl_add_u64 v[230:231], s[40:41], 0, v[136:137]
	global_load_lds_dwordx4 v[2:3], off
	s_mov_b32 m0, s57
	s_nop 0
	global_load_lds_dwordx4 v[228:229], off
	s_mov_b32 m0, s58
	s_nop 0
	global_load_lds_dwordx4 v[230:231], off
	s_waitcnt vmcnt(8)
	s_waitcnt lgkmcnt(0)
	s_barrier
; #define PG8_STAGE(bufoff, gbase, voff) do { _Pragma("unroll") for (int _i = 0; _i < 2; ++_i) \
;         __builtin_amdgcn_global_load_lds((const __attribute__((address_space(1))) unsigned*)((const char*)(gbase) + (voff)[_i]), (LAS unsigned*)(lds + (bufoff) + ldsw + _i * 8192), 16, 0, 0); } while (0)
; #define PG8_LDA(dst, b, h) do { _Pragma("unroll") for (int m = 0; m < 4; ++m) _Pragma("unroll") for (int k = 0; k < 2; ++k) dst[m][k] = *(const LAS bf16x8*)(lds + PG8_SA(b, h) + aoff + m * 2048 + k * 1024); } while (0)
; #define PG8_LDB(dst, b, h) do { _Pragma("unroll") for (int n = 0; n < 2; ++n) _Pragma("unroll") for (int k = 0; k < 2; ++k) dst[n][k] = *(const LAS bf16x8*)(lds + PG8_SB(b, h) + boff + n * 2048 + k * 1024); } while (0)
; #define PG8_MMA(ai, bj, At, Bt) do { __builtin_amdgcn_s_setprio(1); _Pragma("unroll") for (int m = 0; m < 4; ++m) _Pragma("unroll") for (int n = 0; n < 2; ++n) _Pragma("unroll") for (int k = 0; k < 2; ++k) \
;         acc[ai][bj][m][n] = __builtin_amdgcn_mfma_f32_16x16x32_bf16(Bt[n][k], At[m][k], acc[ai][bj][m][n], 0, 0, 0); __builtin_amdgcn_s_setprio(0); } while (0)
; #define PG8_WAIT_V(n) asm volatile("s_waitcnt vmcnt(" #n ")" ::: "memory")
; #define PG8_WAIT_L(n) asm volatile("s_waitcnt lgkmcnt(" #n ")" ::: "memory")
; #define PG8_BAR __builtin_amdgcn_s_barrier()
; #define PG8_SCHED __builtin_amdgcn_sched_barrier(0)
; template <class Epi, class SchedT, bool ALIGN_EPI, bool SP2>
; __device__ __forceinline__ void gemm_phase(LAS unsigned char* lds, const int ldk, const int nt, const SchedT& S, const Epi& E) {
;     ...
;             PG8_WAIT_V(8); PG8_WAIT_L(0); PG8_BAR; PG8_MMA(1, 0, At, B0); PG8_MMA(1, 1, At, B1); PG8_BAR; PG8_SCHED;
;             PG8_LDB(B0, 1, 0); PG8_LDB(B1, 1, 1); PG8_SCHED; PG8_LDA(At, 1, 0); PG8_STAGE(PG8_SA(0, 1), a2 + hstep, voffA);
;             PG8_WAIT_V(8); PG8_WAIT_L(0); PG8_BAR; PG8_MMA(0, 0, At, B0); PG8_MMA(0, 1, At, B1); PG8_BAR; PG8_SCHED;
	s_setprio 1
	s_waitcnt lgkmcnt(0)
	v_mfma_f32_16x16x32_bf16 v[64:67], v[144:147], v[194:197], v[64:67]
	v_mfma_f32_16x16x32_bf16 v[60:63], v[152:155], v[194:197], v[60:63]
	v_mfma_f32_16x16x32_bf16 v[56:59], v[144:147], v[202:205], v[56:59]
	v_mfma_f32_16x16x32_bf16 v[52:55], v[152:155], v[202:205], v[52:55]
	v_mfma_f32_16x16x32_bf16 v[48:51], v[144:147], v[210:213], v[48:51]
	v_mfma_f32_16x16x32_bf16 v[44:47], v[152:155], v[210:213], v[44:47]
	v_mfma_f32_16x16x32_bf16 v[40:43], v[144:147], v[218:221], v[40:43]
	v_mfma_f32_16x16x32_bf16 v[36:39], v[152:155], v[218:221], v[36:39]
	v_mfma_f32_16x16x32_bf16 v[64:67], v[148:151], v[198:201], v[64:67]
	v_mfma_f32_16x16x32_bf16 v[60:63], v[174:177], v[198:201], v[60:63]
	v_mfma_f32_16x16x32_bf16 v[56:59], v[148:151], v[206:209], v[56:59]
	v_mfma_f32_16x16x32_bf16 v[52:55], v[174:177], v[206:209], v[52:55]
	v_mfma_f32_16x16x32_bf16 v[48:51], v[148:151], v[214:217], v[48:51]
	v_mfma_f32_16x16x32_bf16 v[44:47], v[174:177], v[214:217], v[44:47]
	v_mfma_f32_16x16x32_bf16 v[40:43], v[148:151], v[222:225], v[40:43]
	v_mfma_f32_16x16x32_bf16 v[36:39], v[174:177], v[222:225], v[36:39]
	s_setprio 0
	s_setprio 1
	v_mfma_f32_16x16x32_bf16 v[32:35], v[178:181], v[194:197], v[32:35]
	v_mfma_f32_16x16x32_bf16 v[28:31], v[186:189], v[194:197], v[28:31]
	v_mfma_f32_16x16x32_bf16 v[24:27], v[178:181], v[202:205], v[24:27]
	v_mfma_f32_16x16x32_bf16 v[20:23], v[186:189], v[202:205], v[20:23]
	v_mfma_f32_16x16x32_bf16 v[16:19], v[178:181], v[210:213], v[16:19]
	v_mfma_f32_16x16x32_bf16 v[12:15], v[186:189], v[210:213], v[12:15]
	v_mfma_f32_16x16x32_bf16 v[8:11], v[178:181], v[218:221], v[8:11]
	v_mfma_f32_16x16x32_bf16 v[2:5], v[186:189], v[218:221], v[4:7]
	v_mfma_f32_16x16x32_bf16 v[32:35], v[182:185], v[198:201], v[32:35]
	v_mfma_f32_16x16x32_bf16 v[28:31], v[190:193], v[198:201], v[28:31]
	v_mfma_f32_16x16x32_bf16 v[24:27], v[182:185], v[206:209], v[24:27]
	v_mfma_f32_16x16x32_bf16 v[20:23], v[190:193], v[206:209], v[20:23]
	v_mfma_f32_16x16x32_bf16 v[16:19], v[182:185], v[214:217], v[16:19]
	v_mfma_f32_16x16x32_bf16 v[12:15], v[190:193], v[214:217], v[12:15]
	v_mfma_f32_16x16x32_bf16 v[8:11], v[182:185], v[222:225], v[8:11]
	v_mfma_f32_16x16x32_bf16 v[2:5], v[190:193], v[222:225], v[2:5]
	s_setprio 0
	s_barrier
	s_add_i32 s49, 0, 0x18000
	v_add_u32_e32 v0, s49, v159
	s_add_i32 s51, 0, 0x1c000
	ds_read_b128 v[144:147], v0
	ds_read_b128 v[148:151], v0 offset:1024
	ds_read_b128 v[152:155], v0 offset:2048
	ds_read_b128 v[174:177], v0 offset:3072
	v_add_u32_e32 v0, s51, v159
	ds_read_b128 v[178:181], v0
	ds_read_b128 v[182:185], v0 offset:1024
	ds_read_b128 v[186:189], v0 offset:2048
	ds_read_b128 v[190:193], v0 offset:3072
	s_add_u32 s40, s40, 0x80000
	s_addc_u32 s41, s41, 0
	s_mov_b32 m0, s59
	v_lshl_add_u64 v[6:7], s[40:41], 0, v[132:133]
	ds_read_b128 v[194:197], v161 offset:32768
	ds_read_b128 v[198:201], v161 offset:33792
	ds_read_b128 v[202:205], v161 offset:34816
	ds_read_b128 v[206:209], v161 offset:35840
	ds_read_b128 v[210:213], v161 offset:36864
	ds_read_b128 v[214:217], v161 offset:37888
	ds_read_b128 v[218:221], v161 offset:38912
	ds_read_b128 v[222:225], v161 offset:39936
	global_load_lds_dwordx4 v[6:7], off
	v_lshl_add_u64 v[6:7], s[40:41], 0, v[136:137]
	s_mov_b32 m0, s60
	s_nop 0
	global_load_lds_dwordx4 v[6:7], off
	s_nop 0
	s_waitcnt vmcnt(8)
	s_waitcnt lgkmcnt(0)
	s_barrier
	s_setprio 1
	s_waitcnt lgkmcnt(0)
	v_mfma_f32_16x16x32_bf16 v[128:131], v[144:147], v[194:197], v[128:131]
	v_mfma_f32_16x16x32_bf16 v[124:127], v[152:155], v[194:197], v[124:127]
	v_mfma_f32_16x16x32_bf16 v[120:123], v[144:147], v[202:205], v[120:123]
	v_mfma_f32_16x16x32_bf16 v[116:119], v[152:155], v[202:205], v[116:119]
	v_mfma_f32_16x16x32_bf16 v[112:115], v[144:147], v[210:213], v[112:115]
	v_mfma_f32_16x16x32_bf16 v[108:111], v[152:155], v[210:213], v[108:111]
	v_mfma_f32_16x16x32_bf16 v[104:107], v[144:147], v[218:221], v[104:107]
	v_mfma_f32_16x16x32_bf16 v[100:103], v[152:155], v[218:221], v[100:103]
	v_mfma_f32_16x16x32_bf16 v[128:131], v[148:151], v[198:201], v[128:131]
	v_mfma_f32_16x16x32_bf16 v[124:127], v[174:177], v[198:201], v[124:127]
	v_mfma_f32_16x16x32_bf16 v[120:123], v[148:151], v[206:209], v[120:123]
	v_mfma_f32_16x16x32_bf16 v[116:119], v[174:177], v[206:209], v[116:119]
	v_mfma_f32_16x16x32_bf16 v[112:115], v[148:151], v[214:217], v[112:115]
	v_mfma_f32_16x16x32_bf16 v[108:111], v[174:177], v[214:217], v[108:111]
	v_mfma_f32_16x16x32_bf16 v[104:107], v[148:151], v[222:225], v[104:107]
	v_mfma_f32_16x16x32_bf16 v[100:103], v[174:177], v[222:225], v[100:103]
	s_setprio 0
	s_setprio 1
	v_mfma_f32_16x16x32_bf16 v[96:99], v[178:181], v[194:197], v[96:99]
	v_mfma_f32_16x16x32_bf16 v[92:95], v[186:189], v[194:197], v[92:95]
	v_mfma_f32_16x16x32_bf16 v[88:91], v[178:181], v[202:205], v[88:91]
	v_mfma_f32_16x16x32_bf16 v[84:87], v[186:189], v[202:205], v[84:87]
	v_mfma_f32_16x16x32_bf16 v[80:83], v[178:181], v[210:213], v[80:83]
	v_mfma_f32_16x16x32_bf16 v[76:79], v[186:189], v[210:213], v[76:79]
	v_mfma_f32_16x16x32_bf16 v[72:75], v[178:181], v[218:221], v[72:75]
	v_mfma_f32_16x16x32_bf16 v[68:71], v[186:189], v[218:221], v[68:71]
	v_mfma_f32_16x16x32_bf16 v[96:99], v[182:185], v[198:201], v[96:99]
	v_mfma_f32_16x16x32_bf16 v[92:95], v[190:193], v[198:201], v[92:95]
	v_mfma_f32_16x16x32_bf16 v[88:91], v[182:185], v[206:209], v[88:91]
	v_mfma_f32_16x16x32_bf16 v[84:87], v[190:193], v[206:209], v[84:87]
	v_mfma_f32_16x16x32_bf16 v[80:83], v[182:185], v[214:217], v[80:83]
	v_mfma_f32_16x16x32_bf16 v[76:79], v[190:193], v[214:217], v[76:79]
	v_mfma_f32_16x16x32_bf16 v[72:75], v[182:185], v[222:225], v[72:75]
	v_mfma_f32_16x16x32_bf16 v[68:71], v[190:193], v[222:225], v[68:71]
	s_setprio 0
	s_barrier
; #define PG8_STAGE(bufoff, gbase, voff) do { _Pragma("unroll") for (int _i = 0; _i < 2; ++_i) \
;         __builtin_amdgcn_global_load_lds((const __attribute__((address_space(1))) unsigned*)((const char*)(gbase) + (voff)[_i]), (LAS unsigned*)(lds + (bufoff) + ldsw + _i * 8192), 16, 0, 0); } while (0)
; #define PG8_LDA(dst, b, h) do { _Pragma("unroll") for (int m = 0; m < 4; ++m) _Pragma("unroll") for (int k = 0; k < 2; ++k) dst[m][k] = *(const LAS bf16x8*)(lds + PG8_SA(b, h) + aoff + m * 2048 + k * 1024); } while (0)
; #define PG8_MMA(ai, bj, At, Bt) do { __builtin_amdgcn_s_setprio(1); _Pragma("unroll") for (int m = 0; m < 4; ++m) _Pragma("unroll") for (int n = 0; n < 2; ++n) _Pragma("unroll") for (int k = 0; k < 2; ++k) \
;         acc[ai][bj][m][n] = __builtin_amdgcn_mfma_f32_16x16x32_bf16(Bt[n][k], At[m][k], acc[ai][bj][m][n], 0, 0, 0); __builtin_amdgcn_s_setprio(0); } while (0)
; #define PG8_WAIT_V(n) asm volatile("s_waitcnt vmcnt(" #n ")" ::: "memory")
; #define PG8_WAIT_L(n) asm volatile("s_waitcnt lgkmcnt(" #n ")" ::: "memory")
; #define PG8_BAR __builtin_amdgcn_s_barrier()
; #define PG8_SCHED __builtin_amdgcn_sched_barrier(0)
; template <class Epi, class SchedT, bool ALIGN_EPI, bool SP2>
; __device__ __forceinline__ void gemm_phase(LAS unsigned char* lds, const int ldk, const int nt, const SchedT& S, const Epi& E) {
;     ...
;             PG8_LDA(At, 1, 1); PG8_STAGE(PG8_SB(1, 0), b3, voffB); PG8_STAGE(PG8_SB(1, 1), b3 + hstepB, voffB); PG8_STAGE(PG8_SA(1, 0), a3, voffA);
;             PG8_WAIT_V(8); PG8_WAIT_L(0); PG8_BAR; PG8_MMA(1, 0, At, B0); PG8_MMA(1, 1, At, B1); PG8_BAR; PG8_SCHED;
;     ...
;         }
;         if constexpr (ALIGN_EPI) { if (wr == 0) PG8_BAR; }
	s_add_i32 s40, s49, s56
	v_lshl_add_u64 v[6:7], v[156:157], 0, s[24:25]
	s_mov_b32 m0, s40
	ds_read_b128 v[194:197], v161 offset:49152
	ds_read_b128 v[198:201], v161 offset:50176
	ds_read_b128 v[202:205], v161 offset:51200
	ds_read_b128 v[206:209], v161 offset:52224
	ds_read_b128 v[210:213], v161 offset:53248
	ds_read_b128 v[214:217], v161 offset:54272
	ds_read_b128 v[218:221], v161 offset:55296
	ds_read_b128 v[222:225], v161 offset:56320
	global_load_lds_dwordx4 v[6:7], off
	s_add_i32 m0, s40, 0x2000
	s_add_u32 s36, s36, 0x20080
	v_lshl_add_u64 v[6:7], v[226:227], 0, s[24:25]
	s_addc_u32 s37, s37, 0
	s_add_i32 s40, s51, s56
	global_load_lds_dwordx4 v[6:7], off
	v_lshl_add_u64 v[6:7], s[36:37], 0, v[134:135]
	s_mov_b32 m0, s40
	s_nop 0
	global_load_lds_dwordx4 v[6:7], off
	v_lshl_add_u64 v[6:7], s[36:37], 0, v[138:139]
	s_add_i32 m0, s40, 0x2000
	s_nop 0
	global_load_lds_dwordx4 v[6:7], off
	v_lshl_add_u64 v[6:7], v[228:229], 0, s[24:25]
	s_mov_b32 m0, s61
	s_nop 0
	global_load_lds_dwordx4 v[6:7], off
	v_lshl_add_u64 v[6:7], v[230:231], 0, s[24:25]
	s_mov_b32 m0, s62
	s_nop 0
	global_load_lds_dwordx4 v[6:7], off
	s_waitcnt vmcnt(8)
	s_waitcnt lgkmcnt(0)
	s_barrier
	s_setprio 1
	s_waitcnt lgkmcnt(0)
	v_mfma_f32_16x16x32_bf16 v[64:67], v[144:147], v[194:197], v[64:67]
	v_mfma_f32_16x16x32_bf16 v[60:63], v[152:155], v[194:197], v[60:63]
	v_mfma_f32_16x16x32_bf16 v[56:59], v[144:147], v[202:205], v[56:59]
	v_mfma_f32_16x16x32_bf16 v[52:55], v[152:155], v[202:205], v[52:55]
	v_mfma_f32_16x16x32_bf16 v[48:51], v[144:147], v[210:213], v[48:51]
	v_mfma_f32_16x16x32_bf16 v[44:47], v[152:155], v[210:213], v[44:47]
	v_mfma_f32_16x16x32_bf16 v[40:43], v[144:147], v[218:221], v[40:43]
	v_mfma_f32_16x16x32_bf16 v[36:39], v[152:155], v[218:221], v[36:39]
	v_mfma_f32_16x16x32_bf16 v[64:67], v[148:151], v[198:201], v[64:67]
	v_mfma_f32_16x16x32_bf16 v[60:63], v[174:177], v[198:201], v[60:63]
	v_mfma_f32_16x16x32_bf16 v[56:59], v[148:151], v[206:209], v[56:59]
	v_mfma_f32_16x16x32_bf16 v[52:55], v[174:177], v[206:209], v[52:55]
	v_mfma_f32_16x16x32_bf16 v[48:51], v[148:151], v[214:217], v[48:51]
	v_mfma_f32_16x16x32_bf16 v[44:47], v[174:177], v[214:217], v[44:47]
	v_mfma_f32_16x16x32_bf16 v[40:43], v[148:151], v[222:225], v[40:43]
	v_mfma_f32_16x16x32_bf16 v[36:39], v[174:177], v[222:225], v[36:39]
	s_setprio 0
	s_setprio 1
	v_mfma_f32_16x16x32_bf16 v[32:35], v[178:181], v[194:197], v[32:35]
	v_mfma_f32_16x16x32_bf16 v[28:31], v[186:189], v[194:197], v[28:31]
	v_mfma_f32_16x16x32_bf16 v[24:27], v[178:181], v[202:205], v[24:27]
	v_mfma_f32_16x16x32_bf16 v[20:23], v[186:189], v[202:205], v[20:23]
	v_mfma_f32_16x16x32_bf16 v[16:19], v[178:181], v[210:213], v[16:19]
	v_mfma_f32_16x16x32_bf16 v[12:15], v[186:189], v[210:213], v[12:15]
	v_mfma_f32_16x16x32_bf16 v[6:9], v[178:181], v[218:221], v[8:11]
	v_mfma_f32_16x16x32_bf16 v[2:5], v[186:189], v[218:221], v[2:5]
	v_mfma_f32_16x16x32_bf16 v[32:35], v[182:185], v[198:201], v[32:35]
	v_mfma_f32_16x16x32_bf16 v[28:31], v[190:193], v[198:201], v[28:31]
	v_mfma_f32_16x16x32_bf16 v[24:27], v[182:185], v[206:209], v[24:27]
	v_mfma_f32_16x16x32_bf16 v[20:23], v[190:193], v[206:209], v[20:23]
	v_mfma_f32_16x16x32_bf16 v[16:19], v[182:185], v[214:217], v[16:19]
	v_mfma_f32_16x16x32_bf16 v[12:15], v[190:193], v[214:217], v[12:15]
	v_mfma_f32_16x16x32_bf16 v[8:11], v[182:185], v[222:225], v[6:9]
	v_mfma_f32_16x16x32_bf16 v[4:7], v[190:193], v[222:225], v[2:5]
	s_setprio 0
	s_barrier
	s_add_i32 s47, s47, 2
	s_add_u32 s34, s34, 0x100
	s_addc_u32 s35, s35, 0
	s_add_u32 s17, s17, 0x100
	s_addc_u32 s20, s20, 0
	s_cmp_gt_u32 s47, 13
	s_cbranch_scc0 .LBB0_534
	s_and_b64 vcc, exec, s[44:45]
	s_cbranch_vccz .LBB0_537
	s_barrier

; #define PG8_STAGE(bufoff, gbase, voff) do { _Pragma("unroll") for (int _i = 0; _i < 2; ++_i) \
;         __builtin_amdgcn_global_load_lds((const __attribute__((address_space(1))) unsigned*)((const char*)(gbase) + (voff)[_i]), (LAS unsigned*)(lds + (bufoff) + ldsw + _i * 8192), 16, 0, 0); } while (0)
; #define PG8_LDA(dst, b, h) do { _Pragma("unroll") for (int m = 0; m < 4; ++m) _Pragma("unroll") for (int k = 0; k < 2; ++k) dst[m][k] = *(const LAS bf16x8*)(lds + PG8_SA(b, h) + aoff + m * 2048 + k * 1024); } while (0)
; #define PG8_LDB(dst, b, h) do { _Pragma("unroll") for (int n = 0; n < 2; ++n) _Pragma("unroll") for (int k = 0; k < 2; ++k) dst[n][k] = *(const LAS bf16x8*)(lds + PG8_SB(b, h) + boff + n * 2048 + k * 1024); } while (0)
; #define PG8_MMA(ai, bj, At, Bt) do { __builtin_amdgcn_s_setprio(1); _Pragma("unroll") for (int m = 0; m < 4; ++m) _Pragma("unroll") for (int n = 0; n < 2; ++n) _Pragma("unroll") for (int k = 0; k < 2; ++k) \
;         acc[ai][bj][m][n] = __builtin_amdgcn_mfma_f32_16x16x32_bf16(Bt[n][k], At[m][k], acc[ai][bj][m][n], 0, 0, 0); __builtin_amdgcn_s_setprio(0); } while (0)
; #define PG8_WAIT_V(n) asm volatile("s_waitcnt vmcnt(" #n ")" ::: "memory")
; #define PG8_WAIT_L(n) asm volatile("s_waitcnt lgkmcnt(" #n ")" ::: "memory")
; #define PG8_BAR __builtin_amdgcn_s_barrier()
; template <class Epi, class SchedT, bool ALIGN_EPI, bool SP2>
; __device__ __forceinline__ void gemm_phase(LAS unsigned char* lds, const int ldk, const int nt, const SchedT& S, const Epi& E) {
;     ...
;             const bool last = (t == nt - 2);
;             const char* a1 = cA + (size_t)(t + 1) * kstep;
;             const char* a2 = last ? nA : cA + (size_t)(t + 2) * kstep; const char* b2 = last ? nB : cB + (size_t)(t + 2) * kstep;
;             const char* a3 = a2 + kstep; const char* b3 = b2 + kstep;
;             if constexpr (SP2) {
;             PG8_LDB(B0, 0, 0); PG8_LDB(B1, 0, 1); PG8_SCHED; PG8_LDA(At, 0, 0); PG8_STAGE(PG8_SA(1, 1), a1 + hstep, voffA);
;             PG8_WAIT_V(8); PG8_WAIT_L(0); PG8_BAR; PG8_MMA(0, 0, At, B0); PG8_MMA(0, 1, At, B1); PG8_BAR; PG8_SCHED;
;             PG8_LDA(At, 0, 1); PG8_STAGE(PG8_SB(0, 0), b2, voffB); PG8_STAGE(PG8_SB(0, 1), b2 + hstepB, voffB); PG8_STAGE(PG8_SA(0, 0), a2, voffA);
;             PG8_WAIT_V(8); PG8_WAIT_L(0); PG8_BAR; PG8_MMA(1, 0, At, B0); PG8_MMA(1, 1, At, B1); PG8_BAR; PG8_SCHED;
.LBB0_668:
	s_add_u32 s36, s34, 0xfff80080
	s_addc_u32 s37, s35, -1
	s_add_i32 s51, 0, 0x10000
	s_cmp_eq_u32 s22, 28
	s_cselect_b32 s57, s1, s37
	s_cselect_b32 s56, s0, s36
	v_add_u32_e32 v144, s51, v147
	s_cselect_b32 s37, s55, s20
	s_cselect_b32 s36, s54, s13
	s_add_i32 s53, 0, 0x14000
	ds_read_b128 v[140:143], v144
	ds_read_b128 v[150:153], v144 offset:1024
	ds_read_b128 v[154:157], v144 offset:2048
	ds_read_b128 v[158:161], v144 offset:3072
	v_add_u32_e32 v144, s53, v147
	ds_read_b128 v[174:177], v144
	ds_read_b128 v[178:181], v144 offset:1024
	ds_read_b128 v[182:185], v144 offset:2048
	ds_read_b128 v[186:189], v144 offset:3072
	v_lshl_add_u64 v[144:145], s[34:35], 0, v[136:137]
	s_add_i32 m0, s17, 0xc000
	ds_read_b128 v[190:193], v149
	ds_read_b128 v[194:197], v149 offset:1024
	ds_read_b128 v[198:201], v149 offset:2048
	ds_read_b128 v[202:205], v149 offset:3072
	ds_read_b128 v[206:209], v149 offset:4096
	ds_read_b128 v[210:213], v149 offset:5120
	ds_read_b128 v[214:217], v149 offset:6144
	ds_read_b128 v[218:221], v149 offset:7168
	global_load_lds_dwordx4 v[144:145], off
	v_lshl_add_u64 v[144:145], s[34:35], 0, v[138:139]
	s_add_i32 m0, s17, 0xe000
	s_nop 0
	global_load_lds_dwordx4 v[144:145], off
	s_nop 0
	s_nop 0
	s_nop 0
	s_waitcnt vmcnt(8)
	s_waitcnt lgkmcnt(0)
	s_barrier
	s_setprio 1
	s_waitcnt lgkmcnt(0)
	v_mfma_f32_16x16x32_bf16 v[126:129], v[140:143], v[190:193], v[126:129]
	v_mfma_f32_16x16x32_bf16 v[122:125], v[154:157], v[190:193], v[122:125]
	v_mfma_f32_16x16x32_bf16 v[110:113], v[140:143], v[198:201], v[110:113]
	v_mfma_f32_16x16x32_bf16 v[106:109], v[154:157], v[198:201], v[106:109]
	v_mfma_f32_16x16x32_bf16 v[94:97], v[140:143], v[206:209], v[94:97]
	v_mfma_f32_16x16x32_bf16 v[90:93], v[154:157], v[206:209], v[90:93]
	v_mfma_f32_16x16x32_bf16 v[78:81], v[140:143], v[214:217], v[78:81]
	v_mfma_f32_16x16x32_bf16 v[74:77], v[154:157], v[214:217], v[74:77]
	v_mfma_f32_16x16x32_bf16 v[126:129], v[150:153], v[194:197], v[126:129]
	v_mfma_f32_16x16x32_bf16 v[122:125], v[158:161], v[194:197], v[122:125]
	v_mfma_f32_16x16x32_bf16 v[110:113], v[150:153], v[202:205], v[110:113]
	v_mfma_f32_16x16x32_bf16 v[106:109], v[158:161], v[202:205], v[106:109]
	v_mfma_f32_16x16x32_bf16 v[94:97], v[150:153], v[210:213], v[94:97]
	v_mfma_f32_16x16x32_bf16 v[90:93], v[158:161], v[210:213], v[90:93]
	v_mfma_f32_16x16x32_bf16 v[78:81], v[150:153], v[218:221], v[78:81]
	v_mfma_f32_16x16x32_bf16 v[74:77], v[158:161], v[218:221], v[74:77]
	s_setprio 0
	s_setprio 1
	v_mfma_f32_16x16x32_bf16 v[118:121], v[174:177], v[190:193], v[118:121]
	v_mfma_f32_16x16x32_bf16 v[114:117], v[182:185], v[190:193], v[114:117]
	v_mfma_f32_16x16x32_bf16 v[102:105], v[174:177], v[198:201], v[102:105]
	v_mfma_f32_16x16x32_bf16 v[98:101], v[182:185], v[198:201], v[98:101]
	v_mfma_f32_16x16x32_bf16 v[86:89], v[174:177], v[206:209], v[86:89]
	v_mfma_f32_16x16x32_bf16 v[82:85], v[182:185], v[206:209], v[82:85]
	v_mfma_f32_16x16x32_bf16 v[70:73], v[174:177], v[214:217], v[70:73]
	v_mfma_f32_16x16x32_bf16 v[66:69], v[182:185], v[214:217], v[66:69]
	v_mfma_f32_16x16x32_bf16 v[118:121], v[178:181], v[194:197], v[118:121]
	v_mfma_f32_16x16x32_bf16 v[114:117], v[186:189], v[194:197], v[114:117]
	v_mfma_f32_16x16x32_bf16 v[102:105], v[178:181], v[202:205], v[102:105]
	v_mfma_f32_16x16x32_bf16 v[98:101], v[186:189], v[202:205], v[98:101]
	v_mfma_f32_16x16x32_bf16 v[86:89], v[178:181], v[210:213], v[86:89]
	v_mfma_f32_16x16x32_bf16 v[82:85], v[186:189], v[210:213], v[82:85]
	v_mfma_f32_16x16x32_bf16 v[70:73], v[178:181], v[218:221], v[70:73]
	v_mfma_f32_16x16x32_bf16 v[66:69], v[186:189], v[218:221], v[66:69]
	s_setprio 0
	s_barrier
	s_add_i32 s51, s51, s61
	v_lshl_add_u64 v[144:145], s[36:37], 0, v[0:1]
	s_mov_b32 m0, s51
	ds_read_b128 v[190:193], v149 offset:16384
	ds_read_b128 v[194:197], v149 offset:17408
	ds_read_b128 v[198:201], v149 offset:18432
	ds_read_b128 v[202:205], v149 offset:19456
	ds_read_b128 v[206:209], v149 offset:20480
	ds_read_b128 v[210:213], v149 offset:21504
	ds_read_b128 v[214:217], v149 offset:22528
	ds_read_b128 v[218:221], v149 offset:23552
	global_load_lds_dwordx4 v[144:145], off
	s_add_i32 m0, s51, 0x2000
	s_add_u32 s86, s36, 0x20000
	v_lshl_add_u64 v[222:223], s[36:37], 0, v[134:135]
	s_addc_u32 s87, s37, 0
	s_add_i32 s51, s53, s61
	global_load_lds_dwordx4 v[222:223], off
	v_lshl_add_u64 v[224:225], s[86:87], 0, v[0:1]
	s_mov_b32 m0, s51
	v_lshl_add_u64 v[226:227], s[56:57], 0, v[132:133]
	global_load_lds_dwordx4 v[224:225], off
	v_lshl_add_u64 v[224:225], s[86:87], 0, v[134:135]
	s_add_i32 m0, s51, 0x2000
	s_nop 0
	global_load_lds_dwordx4 v[224:225], off
	v_lshl_add_u64 v[224:225], s[56:57], 0, v[130:131]
	s_mov_b32 m0, s17
	s_nop 0
	global_load_lds_dwordx4 v[224:225], off
	s_mov_b32 m0, s62
	s_nop 0
	global_load_lds_dwordx4 v[226:227], off
	s_nop 0
	s_waitcnt vmcnt(8)
	s_waitcnt lgkmcnt(0)
	s_barrier
; #define PG8_STAGE(bufoff, gbase, voff) do { _Pragma("unroll") for (int _i = 0; _i < 2; ++_i) \
;         __builtin_amdgcn_global_load_lds((const __attribute__((address_space(1))) unsigned*)((const char*)(gbase) + (voff)[_i]), (LAS unsigned*)(lds + (bufoff) + ldsw + _i * 8192), 16, 0, 0); } while (0)
; #define PG8_LDA(dst, b, h) do { _Pragma("unroll") for (int m = 0; m < 4; ++m) _Pragma("unroll") for (int k = 0; k < 2; ++k) dst[m][k] = *(const LAS bf16x8*)(lds + PG8_SA(b, h) + aoff + m * 2048 + k * 1024); } while (0)
; #define PG8_LDB(dst, b, h) do { _Pragma("unroll") for (int n = 0; n < 2; ++n) _Pragma("unroll") for (int k = 0; k < 2; ++k) dst[n][k] = *(const LAS bf16x8*)(lds + PG8_SB(b, h) + boff + n * 2048 + k * 1024); } while (0)
; #define PG8_MMA(ai, bj, At, Bt) do { __builtin_amdgcn_s_setprio(1); _Pragma("unroll") for (int m = 0; m < 4; ++m) _Pragma("unroll") for (int n = 0; n < 2; ++n) _Pragma("unroll") for (int k = 0; k < 2; ++k) \
;         acc[ai][bj][m][n] = __builtin_amdgcn_mfma_f32_16x16x32_bf16(Bt[n][k], At[m][k], acc[ai][bj][m][n], 0, 0, 0); __builtin_amdgcn_s_setprio(0); } while (0)
; #define PG8_WAIT_V(n) asm volatile("s_waitcnt vmcnt(" #n ")" ::: "memory")
; #define PG8_WAIT_L(n) asm volatile("s_waitcnt lgkmcnt(" #n ")" ::: "memory")
; #define PG8_BAR __builtin_amdgcn_s_barrier()
; #define PG8_SCHED __builtin_amdgcn_sched_barrier(0)
; template <class Epi, class SchedT, bool ALIGN_EPI, bool SP2>
; __device__ __forceinline__ void gemm_phase(LAS unsigned char* lds, const int ldk, const int nt, const SchedT& S, const Epi& E) {
;     ...
;             PG8_WAIT_V(8); PG8_WAIT_L(0); PG8_BAR; PG8_MMA(1, 0, At, B0); PG8_MMA(1, 1, At, B1); PG8_BAR; PG8_SCHED;
;             PG8_LDB(B0, 1, 0); PG8_LDB(B1, 1, 1); PG8_SCHED; PG8_LDA(At, 1, 0); PG8_STAGE(PG8_SA(0, 1), a2 + hstep, voffA);
;             PG8_WAIT_V(8); PG8_WAIT_L(0); PG8_BAR; PG8_MMA(0, 0, At, B0); PG8_MMA(0, 1, At, B1); PG8_BAR; PG8_SCHED;
	s_setprio 1
	s_waitcnt lgkmcnt(0)
	v_mfma_f32_16x16x32_bf16 v[62:65], v[140:143], v[190:193], v[62:65]
	v_mfma_f32_16x16x32_bf16 v[58:61], v[154:157], v[190:193], v[58:61]
	v_mfma_f32_16x16x32_bf16 v[46:49], v[140:143], v[198:201], v[46:49]
	v_mfma_f32_16x16x32_bf16 v[42:45], v[154:157], v[198:201], v[42:45]
	v_mfma_f32_16x16x32_bf16 v[30:33], v[140:143], v[206:209], v[30:33]
	v_mfma_f32_16x16x32_bf16 v[26:29], v[154:157], v[206:209], v[26:29]
	v_mfma_f32_16x16x32_bf16 v[14:17], v[140:143], v[214:217], v[14:17]
	v_mfma_f32_16x16x32_bf16 v[10:13], v[154:157], v[214:217], v[10:13]
	v_mfma_f32_16x16x32_bf16 v[62:65], v[150:153], v[194:197], v[62:65]
	v_mfma_f32_16x16x32_bf16 v[58:61], v[158:161], v[194:197], v[58:61]
	v_mfma_f32_16x16x32_bf16 v[46:49], v[150:153], v[202:205], v[46:49]
	v_mfma_f32_16x16x32_bf16 v[42:45], v[158:161], v[202:205], v[42:45]
	v_mfma_f32_16x16x32_bf16 v[30:33], v[150:153], v[210:213], v[30:33]
	v_mfma_f32_16x16x32_bf16 v[26:29], v[158:161], v[210:213], v[26:29]
	v_mfma_f32_16x16x32_bf16 v[14:17], v[150:153], v[218:221], v[14:17]
	v_mfma_f32_16x16x32_bf16 v[10:13], v[158:161], v[218:221], v[10:13]
	s_setprio 0
	s_setprio 1
	v_mfma_f32_16x16x32_bf16 v[54:57], v[174:177], v[190:193], v[54:57]
	v_mfma_f32_16x16x32_bf16 v[50:53], v[182:185], v[190:193], v[50:53]
	v_mfma_f32_16x16x32_bf16 v[38:41], v[174:177], v[198:201], v[38:41]
	v_mfma_f32_16x16x32_bf16 v[34:37], v[182:185], v[198:201], v[34:37]
	v_mfma_f32_16x16x32_bf16 v[22:25], v[174:177], v[206:209], v[22:25]
	v_mfma_f32_16x16x32_bf16 v[18:21], v[182:185], v[206:209], v[18:21]
	v_mfma_f32_16x16x32_bf16 v[6:9], v[174:177], v[214:217], v[6:9]
	v_mfma_f32_16x16x32_bf16 v[2:5], v[182:185], v[214:217], v[2:5]
	v_mfma_f32_16x16x32_bf16 v[54:57], v[178:181], v[194:197], v[54:57]
	v_mfma_f32_16x16x32_bf16 v[50:53], v[186:189], v[194:197], v[50:53]
	v_mfma_f32_16x16x32_bf16 v[38:41], v[178:181], v[202:205], v[38:41]
	v_mfma_f32_16x16x32_bf16 v[34:37], v[186:189], v[202:205], v[34:37]
	v_mfma_f32_16x16x32_bf16 v[22:25], v[178:181], v[210:213], v[22:25]
	v_mfma_f32_16x16x32_bf16 v[18:21], v[186:189], v[210:213], v[18:21]
	v_mfma_f32_16x16x32_bf16 v[6:9], v[178:181], v[218:221], v[6:9]
	v_mfma_f32_16x16x32_bf16 v[2:5], v[186:189], v[218:221], v[2:5]
	s_setprio 0
	s_barrier
	s_add_i32 s51, 0, 0x18000
	s_add_i32 s53, 0, 0x1c000
	v_add_u32_e32 v158, s51, v147
	v_add_u32_e32 v186, s53, v147
	ds_read_b128 v[140:143], v158
	ds_read_b128 v[150:153], v158 offset:1024
	ds_read_b128 v[154:157], v158 offset:2048
	ds_read_b128 v[158:161], v158 offset:3072
	ds_read_b128 v[174:177], v186
	ds_read_b128 v[178:181], v186 offset:1024
	ds_read_b128 v[182:185], v186 offset:2048
	ds_read_b128 v[186:189], v186 offset:3072
	s_add_u32 s56, s56, 0x80000
	s_addc_u32 s57, s57, 0
	s_mov_b32 m0, s63
	v_lshl_add_u64 v[228:229], s[56:57], 0, v[130:131]
	ds_read_b128 v[190:193], v149 offset:32768
	ds_read_b128 v[194:197], v149 offset:33792
	ds_read_b128 v[198:201], v149 offset:34816
	ds_read_b128 v[202:205], v149 offset:35840
	ds_read_b128 v[206:209], v149 offset:36864
	ds_read_b128 v[210:213], v149 offset:37888
	ds_read_b128 v[214:217], v149 offset:38912
	ds_read_b128 v[218:221], v149 offset:39936
	global_load_lds_dwordx4 v[228:229], off
	v_lshl_add_u64 v[228:229], s[56:57], 0, v[132:133]
	s_mov_b32 m0, s81
	s_nop 0
	global_load_lds_dwordx4 v[228:229], off
	s_nop 0
	s_waitcnt vmcnt(8)
	s_waitcnt lgkmcnt(0)
	s_barrier
	s_setprio 1
	s_waitcnt lgkmcnt(0)
	v_mfma_f32_16x16x32_bf16 v[126:129], v[140:143], v[190:193], v[126:129]
	v_mfma_f32_16x16x32_bf16 v[122:125], v[154:157], v[190:193], v[122:125]
	v_mfma_f32_16x16x32_bf16 v[110:113], v[140:143], v[198:201], v[110:113]
	v_mfma_f32_16x16x32_bf16 v[106:109], v[154:157], v[198:201], v[106:109]
	v_mfma_f32_16x16x32_bf16 v[94:97], v[140:143], v[206:209], v[94:97]
	v_mfma_f32_16x16x32_bf16 v[90:93], v[154:157], v[206:209], v[90:93]
	v_mfma_f32_16x16x32_bf16 v[78:81], v[140:143], v[214:217], v[78:81]
	v_mfma_f32_16x16x32_bf16 v[74:77], v[154:157], v[214:217], v[74:77]
	v_mfma_f32_16x16x32_bf16 v[126:129], v[150:153], v[194:197], v[126:129]
	v_mfma_f32_16x16x32_bf16 v[122:125], v[158:161], v[194:197], v[122:125]
	v_mfma_f32_16x16x32_bf16 v[110:113], v[150:153], v[202:205], v[110:113]
	v_mfma_f32_16x16x32_bf16 v[106:109], v[158:161], v[202:205], v[106:109]
	v_mfma_f32_16x16x32_bf16 v[94:97], v[150:153], v[210:213], v[94:97]
	v_mfma_f32_16x16x32_bf16 v[90:93], v[158:161], v[210:213], v[90:93]
	v_mfma_f32_16x16x32_bf16 v[78:81], v[150:153], v[218:221], v[78:81]
	v_mfma_f32_16x16x32_bf16 v[74:77], v[158:161], v[218:221], v[74:77]
	s_setprio 0
	s_setprio 1
	v_mfma_f32_16x16x32_bf16 v[118:121], v[174:177], v[190:193], v[118:121]
	v_mfma_f32_16x16x32_bf16 v[114:117], v[182:185], v[190:193], v[114:117]
	v_mfma_f32_16x16x32_bf16 v[102:105], v[174:177], v[198:201], v[102:105]
	v_mfma_f32_16x16x32_bf16 v[98:101], v[182:185], v[198:201], v[98:101]
	v_mfma_f32_16x16x32_bf16 v[86:89], v[174:177], v[206:209], v[86:89]
	v_mfma_f32_16x16x32_bf16 v[82:85], v[182:185], v[206:209], v[82:85]
	v_mfma_f32_16x16x32_bf16 v[70:73], v[174:177], v[214:217], v[70:73]
	v_mfma_f32_16x16x32_bf16 v[66:69], v[182:185], v[214:217], v[66:69]
	v_mfma_f32_16x16x32_bf16 v[118:121], v[178:181], v[194:197], v[118:121]
	v_mfma_f32_16x16x32_bf16 v[114:117], v[186:189], v[194:197], v[114:117]
	v_mfma_f32_16x16x32_bf16 v[102:105], v[178:181], v[202:205], v[102:105]
	v_mfma_f32_16x16x32_bf16 v[98:101], v[186:189], v[202:205], v[98:101]
	v_mfma_f32_16x16x32_bf16 v[86:89], v[178:181], v[210:213], v[86:89]
	v_mfma_f32_16x16x32_bf16 v[82:85], v[186:189], v[210:213], v[82:85]
	v_mfma_f32_16x16x32_bf16 v[70:73], v[178:181], v[218:221], v[70:73]
	v_mfma_f32_16x16x32_bf16 v[66:69], v[186:189], v[218:221], v[66:69]
	s_setprio 0
	s_barrier
; #define PG8_STAGE(bufoff, gbase, voff) do { _Pragma("unroll") for (int _i = 0; _i < 2; ++_i) \
;         __builtin_amdgcn_global_load_lds((const __attribute__((address_space(1))) unsigned*)((const char*)(gbase) + (voff)[_i]), (LAS unsigned*)(lds + (bufoff) + ldsw + _i * 8192), 16, 0, 0); } while (0)
; #define PG8_LDA(dst, b, h) do { _Pragma("unroll") for (int m = 0; m < 4; ++m) _Pragma("unroll") for (int k = 0; k < 2; ++k) dst[m][k] = *(const LAS bf16x8*)(lds + PG8_SA(b, h) + aoff + m * 2048 + k * 1024); } while (0)
; #define PG8_MMA(ai, bj, At, Bt) do { __builtin_amdgcn_s_setprio(1); _Pragma("unroll") for (int m = 0; m < 4; ++m) _Pragma("unroll") for (int n = 0; n < 2; ++n) _Pragma("unroll") for (int k = 0; k < 2; ++k) \
;         acc[ai][bj][m][n] = __builtin_amdgcn_mfma_f32_16x16x32_bf16(Bt[n][k], At[m][k], acc[ai][bj][m][n], 0, 0, 0); __builtin_amdgcn_s_setprio(0); } while (0)
; #define PG8_WAIT_V(n) asm volatile("s_waitcnt vmcnt(" #n ")" ::: "memory")
; #define PG8_WAIT_L(n) asm volatile("s_waitcnt lgkmcnt(" #n ")" ::: "memory")
; #define PG8_BAR __builtin_amdgcn_s_barrier()
; #define PG8_SCHED __builtin_amdgcn_sched_barrier(0)
; template <class Epi, class SchedT, bool ALIGN_EPI, bool SP2>
; __device__ __forceinline__ void gemm_phase(LAS unsigned char* lds, const int ldk, const int nt, const SchedT& S, const Epi& E) {
;     ...
;             PG8_LDA(At, 1, 1); PG8_STAGE(PG8_SB(1, 0), b3, voffB); PG8_STAGE(PG8_SB(1, 1), b3 + hstepB, voffB); PG8_STAGE(PG8_SA(1, 0), a3, voffA);
;             PG8_WAIT_V(8); PG8_WAIT_L(0); PG8_BAR; PG8_MMA(1, 0, At, B0); PG8_MMA(1, 1, At, B1); PG8_BAR; PG8_SCHED;
;     __device__ __forceinline__ void operator()(f32x4 (&acc)[2][2][4][2], const Unit& u, int wr, int wc, int fr, int fq) const {
;         const int row0 = u.pm * BM + wr * 64 + fr, col0 = u.pn * BM + wc * 64 + 8 * fq;
; #pragma unroll
;         for (int ai = 0; ai < 2; ++ai)
; #pragma unroll
;             for (int m = 0; m < 4; ++m) {
;                 const int row = row0 + ai * HALF + m * 16; float sq = 0.f;
; #pragma unroll
;                 for (int bj = 0; bj < 2; ++bj) {
;                     const size_t off = (size_t)row * D + col0 + bj * 32;
;                     const u32x4 xw = *(const u32x4*)(xin + off);
	s_add_i32 s51, s51, s61
	v_lshl_add_u64 v[144:145], v[144:145], 0, s[24:25]
	s_mov_b32 m0, s51
	ds_read_b128 v[190:193], v149 offset:49152
	ds_read_b128 v[194:197], v149 offset:50176
	ds_read_b128 v[198:201], v149 offset:51200
	ds_read_b128 v[202:205], v149 offset:52224
	ds_read_b128 v[206:209], v149 offset:53248
	ds_read_b128 v[210:213], v149 offset:54272
	ds_read_b128 v[214:217], v149 offset:55296
	ds_read_b128 v[218:221], v149 offset:56320
	global_load_lds_dwordx4 v[144:145], off
	s_add_i32 m0, s51, 0x2000
	s_add_u32 s36, s36, 0x20080
	v_lshl_add_u64 v[144:145], v[222:223], 0, s[24:25]
	s_addc_u32 s37, s37, 0
	s_add_i32 s51, s53, s61
	global_load_lds_dwordx4 v[144:145], off
	v_lshl_add_u64 v[144:145], s[36:37], 0, v[0:1]
	s_mov_b32 m0, s51
	s_nop 0
	global_load_lds_dwordx4 v[144:145], off
	v_lshl_add_u64 v[144:145], s[36:37], 0, v[134:135]
	s_add_i32 m0, s51, 0x2000
	s_nop 0
	global_load_lds_dwordx4 v[144:145], off
	v_lshl_add_u64 v[144:145], v[224:225], 0, s[24:25]
	s_mov_b32 m0, s83
	s_nop 0
	global_load_lds_dwordx4 v[144:145], off
	v_lshl_add_u64 v[144:145], v[226:227], 0, s[24:25]
	s_mov_b32 m0, s84
	s_nop 0
	global_load_lds_dwordx4 v[144:145], off
	s_waitcnt vmcnt(8)
	s_waitcnt lgkmcnt(0)
	s_barrier
	s_setprio 1
	s_waitcnt lgkmcnt(0)
	v_mfma_f32_16x16x32_bf16 v[62:65], v[140:143], v[190:193], v[62:65]
	v_mfma_f32_16x16x32_bf16 v[58:61], v[154:157], v[190:193], v[58:61]
	v_mfma_f32_16x16x32_bf16 v[46:49], v[140:143], v[198:201], v[46:49]
	v_mfma_f32_16x16x32_bf16 v[42:45], v[154:157], v[198:201], v[42:45]
	v_mfma_f32_16x16x32_bf16 v[30:33], v[140:143], v[206:209], v[30:33]
	v_mfma_f32_16x16x32_bf16 v[26:29], v[154:157], v[206:209], v[26:29]
	v_mfma_f32_16x16x32_bf16 v[14:17], v[140:143], v[214:217], v[14:17]
	v_mfma_f32_16x16x32_bf16 v[10:13], v[154:157], v[214:217], v[10:13]
	v_mfma_f32_16x16x32_bf16 v[62:65], v[150:153], v[194:197], v[62:65]
	v_mfma_f32_16x16x32_bf16 v[58:61], v[158:161], v[194:197], v[58:61]
	v_mfma_f32_16x16x32_bf16 v[46:49], v[150:153], v[202:205], v[46:49]
	v_mfma_f32_16x16x32_bf16 v[42:45], v[158:161], v[202:205], v[42:45]
	v_mfma_f32_16x16x32_bf16 v[30:33], v[150:153], v[210:213], v[30:33]
	v_mfma_f32_16x16x32_bf16 v[26:29], v[158:161], v[210:213], v[26:29]
	v_mfma_f32_16x16x32_bf16 v[14:17], v[150:153], v[218:221], v[14:17]
	v_mfma_f32_16x16x32_bf16 v[10:13], v[158:161], v[218:221], v[10:13]
	s_setprio 0
	s_setprio 1
	v_mfma_f32_16x16x32_bf16 v[54:57], v[174:177], v[190:193], v[54:57]
	v_mfma_f32_16x16x32_bf16 v[50:53], v[182:185], v[190:193], v[50:53]
	v_mfma_f32_16x16x32_bf16 v[38:41], v[174:177], v[198:201], v[38:41]
	v_mfma_f32_16x16x32_bf16 v[34:37], v[182:185], v[198:201], v[34:37]
	v_mfma_f32_16x16x32_bf16 v[22:25], v[174:177], v[206:209], v[22:25]
	v_mfma_f32_16x16x32_bf16 v[18:21], v[182:185], v[206:209], v[18:21]
	v_mfma_f32_16x16x32_bf16 v[6:9], v[174:177], v[214:217], v[6:9]
	v_mfma_f32_16x16x32_bf16 v[2:5], v[182:185], v[214:217], v[2:5]
	v_mfma_f32_16x16x32_bf16 v[54:57], v[178:181], v[194:197], v[54:57]
	v_mfma_f32_16x16x32_bf16 v[50:53], v[186:189], v[194:197], v[50:53]
	v_mfma_f32_16x16x32_bf16 v[38:41], v[178:181], v[202:205], v[38:41]
	v_mfma_f32_16x16x32_bf16 v[34:37], v[186:189], v[202:205], v[34:37]
	v_mfma_f32_16x16x32_bf16 v[22:25], v[178:181], v[210:213], v[22:25]
	v_mfma_f32_16x16x32_bf16 v[18:21], v[186:189], v[210:213], v[18:21]
	v_mfma_f32_16x16x32_bf16 v[6:9], v[178:181], v[218:221], v[6:9]
	v_mfma_f32_16x16x32_bf16 v[2:5], v[186:189], v[218:221], v[2:5]
	s_setprio 0
	s_barrier
	s_add_i32 s22, s22, 2
	s_add_u32 s34, s34, 0x100
	s_addc_u32 s35, s35, 0
	s_add_u32 s13, s13, 0x100
	s_addc_u32 s20, s20, 0
	s_cmp_gt_u32 s22, 29
	s_cbranch_scc0 .LBB0_668
	v_lshl_add_u32 v142, s16, 8, v146
	v_lshl_or_b32 v140, s12, 8, v148
	v_lshlrev_b32_e32 v141, 12, v142
	v_lshl_add_u32 v150, v140, 1, v141
	v_add_u32_e32 v151, 0x10000, v150
	v_add_u32_e32 v152, 0x20000, v150
	v_add_u32_e32 v153, 0x30000, v150
	v_add_u32_e32 v154, 0x80000, v150
	v_add_u32_e32 v155, 0x90000, v150
	v_add_u32_e32 v156, 0xa0000, v150
	v_add_u32_e32 v157, 0xb0000, v150
	global_load_dwordx4 v[174:177], v150, s[42:43]
	global_load_dwordx4 v[178:181], v150, s[42:43] offset:64
	global_load_dwordx4 v[182:185], v151, s[42:43]
	global_load_dwordx4 v[186:189], v151, s[42:43] offset:64
	global_load_dwordx4 v[190:193], v152, s[42:43]
	global_load_dwordx4 v[194:197], v152, s[42:43] offset:64
	global_load_dwordx4 v[198:201], v153, s[42:43]
	global_load_dwordx4 v[202:205], v153, s[42:43] offset:64
	global_load_dwordx4 v[206:209], v154, s[42:43]
	global_load_dwordx4 v[210:213], v154, s[42:43] offset:64
	global_load_dwordx4 v[214:217], v155, s[42:43]
	global_load_dwordx4 v[218:221], v155, s[42:43] offset:64
	global_load_dwordx4 v[222:225], v156, s[42:43]
	global_load_dwordx4 v[226:229], v156, s[42:43] offset:64
	global_load_dwordx4 v[230:233], v157, s[42:43]
	global_load_dwordx4 v[234:237], v157, s[42:43] offset:64
	s_lshl_b32 s56, s12, 4
	s_lshl_b32 s22, s82, 2
	s_add_i32 s56, s56, s22
	v_lshl_add_u32 v158, v142, 7, s56
	v_add_u32_e32 v159, 0x1000, v158
	v_add_u32_e32 v160, 0x4000, v158
	v_add_u32_e32 v161, 0x5000, v158
	v_xor_b32_e32 v239, 16, v241
	v_xor_b32_e32 v252, 32, v241
	v_lshlrev_b32_e32 v239, 2, v239
	v_lshlrev_b32_e32 v252, 2, v252
	s_and_b64 vcc, exec, s[48:49]
	s_cbranch_vccz .LBB0_671
	s_barrier

; #define PG8_STAGE(bufoff, gbase, voff) do { _Pragma("unroll") for (int _i = 0; _i < 2; ++_i) \
;         __builtin_amdgcn_global_load_lds((const __attribute__((address_space(1))) unsigned*)((const char*)(gbase) + (voff)[_i]), (LAS unsigned*)(lds + (bufoff) + ldsw + _i * 8192), 16, 0, 0); } while (0)
; #define PG8_LDA(dst, b, h) do { _Pragma("unroll") for (int m = 0; m < 4; ++m) _Pragma("unroll") for (int k = 0; k < 2; ++k) dst[m][k] = *(const LAS bf16x8*)(lds + PG8_SA(b, h) + aoff + m * 2048 + k * 1024); } while (0)
; #define PG8_LDB(dst, b, h) do { _Pragma("unroll") for (int n = 0; n < 2; ++n) _Pragma("unroll") for (int k = 0; k < 2; ++k) dst[n][k] = *(const LAS bf16x8*)(lds + PG8_SB(b, h) + boff + n * 2048 + k * 1024); } while (0)
; #define PG8_MMA(ai, bj, At, Bt) do { __builtin_amdgcn_s_setprio(1); _Pragma("unroll") for (int m = 0; m < 4; ++m) _Pragma("unroll") for (int n = 0; n < 2; ++n) _Pragma("unroll") for (int k = 0; k < 2; ++k) \
;         acc[ai][bj][m][n] = __builtin_amdgcn_mfma_f32_16x16x32_bf16(Bt[n][k], At[m][k], acc[ai][bj][m][n], 0, 0, 0); __builtin_amdgcn_s_setprio(0); } while (0)
; #define PG8_WAIT_V(n) asm volatile("s_waitcnt vmcnt(" #n ")" ::: "memory")
; #define PG8_WAIT_L(n) asm volatile("s_waitcnt lgkmcnt(" #n ")" ::: "memory")
; #define PG8_BAR __builtin_amdgcn_s_barrier()
; template <class Epi, class SchedT, bool ALIGN_EPI, bool SP2>
; __device__ __forceinline__ void gemm_phase(LAS unsigned char* lds, const int ldk, const int nt, const SchedT& S, const Epi& E) {
;     ...
;             const bool last = (t == nt - 2);
;             const char* a1 = cA + (size_t)(t + 1) * kstep;
;             const char* a2 = last ? nA : cA + (size_t)(t + 2) * kstep; const char* b2 = last ? nB : cB + (size_t)(t + 2) * kstep;
;             const char* a3 = a2 + kstep; const char* b3 = b2 + kstep;
;             if constexpr (SP2) {
;             PG8_LDB(B0, 0, 0); PG8_LDB(B1, 0, 1); PG8_SCHED; PG8_LDA(At, 0, 0); PG8_STAGE(PG8_SA(1, 1), a1 + hstep, voffA);
;             PG8_WAIT_V(8); PG8_WAIT_L(0); PG8_BAR; PG8_MMA(0, 0, At, B0); PG8_MMA(0, 1, At, B1); PG8_BAR; PG8_SCHED;
;             PG8_LDA(At, 0, 1); PG8_STAGE(PG8_SB(0, 0), b2, voffB); PG8_STAGE(PG8_SB(0, 1), b2 + hstepB, voffB); PG8_STAGE(PG8_SA(0, 0), a2, voffA);
;             PG8_WAIT_V(8); PG8_WAIT_L(0); PG8_BAR; PG8_MMA(1, 0, At, B0); PG8_MMA(1, 1, At, B1); PG8_BAR; PG8_SCHED;
.LBB0_752:
	s_add_u32 s36, s34, 0xfff80080
	s_addc_u32 s37, s35, -1
	s_add_i32 s61, 0, 0x10000
	s_cmp_eq_u32 s59, 28
	s_cselect_b32 vcc_hi, s1, s37
	s_cselect_b32 vcc_lo, s0, s36
	s_cselect_b32 s37, s63, s17
	s_cselect_b32 s36, s62, s13
	s_add_i32 s64, 0, 0x14000
	v_add_u32_e32 v142, s61, v248
	v_add_u32_e32 v182, s64, v248
	ds_read_b128 v[130:133], v142
	ds_read_b128 v[134:137], v142 offset:1024
	ds_read_b128 v[138:141], v142 offset:2048
	ds_read_b128 v[142:145], v142 offset:3072
	ds_read_b128 v[158:161], v182
	ds_read_b128 v[174:177], v182 offset:1024
	ds_read_b128 v[178:181], v182 offset:2048
	ds_read_b128 v[182:185], v182 offset:3072
	v_lshl_add_u64 v[218:219], v[222:223], 0, s[24:25]
	s_mov_b32 m0, s89
	s_nop 0
	global_load_lds_dwordx4 v[218:219], off
	v_lshl_add_u64 v[218:219], v[224:225], 0, s[24:25]
	s_mov_b32 m0, s90
	s_nop 0
	global_load_lds_dwordx4 v[218:219], off
	v_lshl_add_u64 v[218:219], s[34:35], 0, v[154:155]
	s_add_i32 m0, s85, 0xc000
	ds_read_b128 v[186:189], v251
	ds_read_b128 v[190:193], v251 offset:1024
	ds_read_b128 v[194:197], v251 offset:2048
	ds_read_b128 v[198:201], v251 offset:3072
	ds_read_b128 v[202:205], v251 offset:4096
	ds_read_b128 v[206:209], v251 offset:5120
	ds_read_b128 v[210:213], v251 offset:6144
	ds_read_b128 v[214:217], v251 offset:7168
	global_load_lds_dwordx4 v[218:219], off
	v_lshl_add_u64 v[218:219], s[34:35], 0, v[156:157]
	s_add_i32 m0, s85, 0xe000
	s_nop 0
	global_load_lds_dwordx4 v[218:219], off
	s_nop 0
	s_nop 0
	s_nop 0
	s_waitcnt vmcnt(8)
	s_waitcnt lgkmcnt(0)
	s_barrier
	s_setprio 1
	s_waitcnt lgkmcnt(0)
	v_mfma_f32_16x16x32_bf16 v[126:129], v[130:133], v[186:189], v[126:129]
	v_mfma_f32_16x16x32_bf16 v[62:65], v[138:141], v[186:189], v[62:65]
	v_mfma_f32_16x16x32_bf16 v[118:121], v[130:133], v[194:197], v[118:121]
	v_mfma_f32_16x16x32_bf16 v[58:61], v[138:141], v[194:197], v[58:61]
	v_mfma_f32_16x16x32_bf16 v[110:113], v[130:133], v[202:205], v[110:113]
	v_mfma_f32_16x16x32_bf16 v[46:49], v[138:141], v[202:205], v[46:49]
	v_mfma_f32_16x16x32_bf16 v[106:109], v[130:133], v[210:213], v[106:109]
	v_mfma_f32_16x16x32_bf16 v[42:45], v[138:141], v[210:213], v[42:45]
	v_mfma_f32_16x16x32_bf16 v[126:129], v[134:137], v[190:193], v[126:129]
	v_mfma_f32_16x16x32_bf16 v[62:65], v[142:145], v[190:193], v[62:65]
	v_mfma_f32_16x16x32_bf16 v[118:121], v[134:137], v[198:201], v[118:121]
	v_mfma_f32_16x16x32_bf16 v[58:61], v[142:145], v[198:201], v[58:61]
	v_mfma_f32_16x16x32_bf16 v[110:113], v[134:137], v[206:209], v[110:113]
	v_mfma_f32_16x16x32_bf16 v[46:49], v[142:145], v[206:209], v[46:49]
	v_mfma_f32_16x16x32_bf16 v[106:109], v[134:137], v[214:217], v[106:109]
	v_mfma_f32_16x16x32_bf16 v[42:45], v[142:145], v[214:217], v[42:45]
	s_setprio 0
	s_setprio 1
	v_mfma_f32_16x16x32_bf16 v[122:125], v[158:161], v[186:189], v[122:125]
	v_mfma_f32_16x16x32_bf16 v[54:57], v[178:181], v[186:189], v[54:57]
	v_mfma_f32_16x16x32_bf16 v[114:117], v[158:161], v[194:197], v[114:117]
	v_mfma_f32_16x16x32_bf16 v[50:53], v[178:181], v[194:197], v[50:53]
	v_mfma_f32_16x16x32_bf16 v[102:105], v[158:161], v[202:205], v[102:105]
	v_mfma_f32_16x16x32_bf16 v[38:41], v[178:181], v[202:205], v[38:41]
	v_mfma_f32_16x16x32_bf16 v[98:101], v[158:161], v[210:213], v[98:101]
	v_mfma_f32_16x16x32_bf16 v[34:37], v[178:181], v[210:213], v[34:37]
	v_mfma_f32_16x16x32_bf16 v[122:125], v[174:177], v[190:193], v[122:125]
	v_mfma_f32_16x16x32_bf16 v[54:57], v[182:185], v[190:193], v[54:57]
	v_mfma_f32_16x16x32_bf16 v[114:117], v[174:177], v[198:201], v[114:117]
	v_mfma_f32_16x16x32_bf16 v[50:53], v[182:185], v[198:201], v[50:53]
	v_mfma_f32_16x16x32_bf16 v[102:105], v[174:177], v[206:209], v[102:105]
	v_mfma_f32_16x16x32_bf16 v[38:41], v[182:185], v[206:209], v[38:41]
	v_mfma_f32_16x16x32_bf16 v[98:101], v[174:177], v[214:217], v[98:101]
	v_mfma_f32_16x16x32_bf16 v[34:37], v[182:185], v[214:217], v[34:37]
	s_setprio 0
	s_barrier
	s_add_i32 s61, s61, s84
	v_lshl_add_u64 v[218:219], s[36:37], 0, v[0:1]
	s_mov_b32 m0, s61
	ds_read_b128 v[186:189], v251 offset:16384
	ds_read_b128 v[190:193], v251 offset:17408
	ds_read_b128 v[194:197], v251 offset:18432
	ds_read_b128 v[198:201], v251 offset:19456
	ds_read_b128 v[202:205], v251 offset:20480
	ds_read_b128 v[206:209], v251 offset:21504
	ds_read_b128 v[210:213], v251 offset:22528
	ds_read_b128 v[214:217], v251 offset:23552
	global_load_lds_dwordx4 v[218:219], off
	s_add_i32 m0, s61, 0x2000
	s_add_u32 s94, s36, 0x20000
	v_lshl_add_u64 v[220:221], s[36:37], 0, v[150:151]
	s_addc_u32 s95, s37, 0
	s_add_i32 s61, s64, s84
	global_load_lds_dwordx4 v[220:221], off
	v_lshl_add_u64 v[222:223], s[94:95], 0, v[0:1]
	s_mov_b32 m0, s61
	v_lshl_add_u64 v[224:225], vcc, 0, v[148:149]
	global_load_lds_dwordx4 v[222:223], off
	v_lshl_add_u64 v[222:223], s[94:95], 0, v[150:151]
	s_add_i32 m0, s61, 0x2000
	s_nop 0
	global_load_lds_dwordx4 v[222:223], off
	v_lshl_add_u64 v[222:223], vcc, 0, v[146:147]
	s_nop 0
	s_waitcnt vmcnt(6)
	s_waitcnt lgkmcnt(0)
	s_barrier
; #define PG8_STAGE(bufoff, gbase, voff) do { _Pragma("unroll") for (int _i = 0; _i < 2; ++_i) \
;         __builtin_amdgcn_global_load_lds((const __attribute__((address_space(1))) unsigned*)((const char*)(gbase) + (voff)[_i]), (LAS unsigned*)(lds + (bufoff) + ldsw + _i * 8192), 16, 0, 0); } while (0)
; #define PG8_LDA(dst, b, h) do { _Pragma("unroll") for (int m = 0; m < 4; ++m) _Pragma("unroll") for (int k = 0; k < 2; ++k) dst[m][k] = *(const LAS bf16x8*)(lds + PG8_SA(b, h) + aoff + m * 2048 + k * 1024); } while (0)
; #define PG8_LDB(dst, b, h) do { _Pragma("unroll") for (int n = 0; n < 2; ++n) _Pragma("unroll") for (int k = 0; k < 2; ++k) dst[n][k] = *(const LAS bf16x8*)(lds + PG8_SB(b, h) + boff + n * 2048 + k * 1024); } while (0)
; #define PG8_MMA(ai, bj, At, Bt) do { __builtin_amdgcn_s_setprio(1); _Pragma("unroll") for (int m = 0; m < 4; ++m) _Pragma("unroll") for (int n = 0; n < 2; ++n) _Pragma("unroll") for (int k = 0; k < 2; ++k) \
;         acc[ai][bj][m][n] = __builtin_amdgcn_mfma_f32_16x16x32_bf16(Bt[n][k], At[m][k], acc[ai][bj][m][n], 0, 0, 0); __builtin_amdgcn_s_setprio(0); } while (0)
; #define PG8_WAIT_V(n) asm volatile("s_waitcnt vmcnt(" #n ")" ::: "memory")
; #define PG8_WAIT_L(n) asm volatile("s_waitcnt lgkmcnt(" #n ")" ::: "memory")
; #define PG8_BAR __builtin_amdgcn_s_barrier()
; #define PG8_SCHED __builtin_amdgcn_sched_barrier(0)
; template <class Epi, class SchedT, bool ALIGN_EPI, bool SP2>
; __device__ __forceinline__ void gemm_phase(LAS unsigned char* lds, const int ldk, const int nt, const SchedT& S, const Epi& E) {
;     ...
;             PG8_WAIT_V(8); PG8_WAIT_L(0); PG8_BAR; PG8_MMA(1, 0, At, B0); PG8_MMA(1, 1, At, B1); PG8_BAR; PG8_SCHED;
;             PG8_LDB(B0, 1, 0); PG8_LDB(B1, 1, 1); PG8_SCHED; PG8_LDA(At, 1, 0); PG8_STAGE(PG8_SA(0, 1), a2 + hstep, voffA);
;             PG8_WAIT_V(8); PG8_WAIT_L(0); PG8_BAR; PG8_MMA(0, 0, At, B0); PG8_MMA(0, 1, At, B1); PG8_BAR; PG8_SCHED;
	s_setprio 1
	s_waitcnt lgkmcnt(0)
	v_mfma_f32_16x16x32_bf16 v[94:97], v[130:133], v[186:189], v[94:97]
	v_mfma_f32_16x16x32_bf16 v[30:33], v[138:141], v[186:189], v[30:33]
	v_mfma_f32_16x16x32_bf16 v[90:93], v[130:133], v[194:197], v[90:93]
	v_mfma_f32_16x16x32_bf16 v[26:29], v[138:141], v[194:197], v[26:29]
	v_mfma_f32_16x16x32_bf16 v[78:81], v[130:133], v[202:205], v[78:81]
	v_mfma_f32_16x16x32_bf16 v[14:17], v[138:141], v[202:205], v[14:17]
	v_mfma_f32_16x16x32_bf16 v[74:77], v[130:133], v[210:213], v[74:77]
	v_mfma_f32_16x16x32_bf16 v[10:13], v[138:141], v[210:213], v[10:13]
	v_mfma_f32_16x16x32_bf16 v[94:97], v[134:137], v[190:193], v[94:97]
	v_mfma_f32_16x16x32_bf16 v[30:33], v[142:145], v[190:193], v[30:33]
	v_mfma_f32_16x16x32_bf16 v[90:93], v[134:137], v[198:201], v[90:93]
	v_mfma_f32_16x16x32_bf16 v[26:29], v[142:145], v[198:201], v[26:29]
	v_mfma_f32_16x16x32_bf16 v[78:81], v[134:137], v[206:209], v[78:81]
	v_mfma_f32_16x16x32_bf16 v[14:17], v[142:145], v[206:209], v[14:17]
	v_mfma_f32_16x16x32_bf16 v[74:77], v[134:137], v[214:217], v[74:77]
	v_mfma_f32_16x16x32_bf16 v[10:13], v[142:145], v[214:217], v[10:13]
	s_setprio 0
	s_setprio 1
	v_mfma_f32_16x16x32_bf16 v[86:89], v[158:161], v[186:189], v[86:89]
	v_mfma_f32_16x16x32_bf16 v[22:25], v[178:181], v[186:189], v[22:25]
	v_mfma_f32_16x16x32_bf16 v[82:85], v[158:161], v[194:197], v[82:85]
	v_mfma_f32_16x16x32_bf16 v[18:21], v[178:181], v[194:197], v[18:21]
	v_mfma_f32_16x16x32_bf16 v[70:73], v[158:161], v[202:205], v[70:73]
	v_mfma_f32_16x16x32_bf16 v[6:9], v[178:181], v[202:205], v[6:9]
	v_mfma_f32_16x16x32_bf16 v[66:69], v[158:161], v[210:213], v[66:69]
	v_mfma_f32_16x16x32_bf16 v[2:5], v[178:181], v[210:213], v[2:5]
	v_mfma_f32_16x16x32_bf16 v[86:89], v[174:177], v[190:193], v[86:89]
	v_mfma_f32_16x16x32_bf16 v[22:25], v[182:185], v[190:193], v[22:25]
	v_mfma_f32_16x16x32_bf16 v[82:85], v[174:177], v[198:201], v[82:85]
	v_mfma_f32_16x16x32_bf16 v[18:21], v[182:185], v[198:201], v[18:21]
	v_mfma_f32_16x16x32_bf16 v[70:73], v[174:177], v[206:209], v[70:73]
	v_mfma_f32_16x16x32_bf16 v[6:9], v[182:185], v[206:209], v[6:9]
	v_mfma_f32_16x16x32_bf16 v[66:69], v[174:177], v[214:217], v[66:69]
	v_mfma_f32_16x16x32_bf16 v[2:5], v[182:185], v[214:217], v[2:5]
	s_setprio 0
	s_barrier
	s_add_i32 s61, 0, 0x18000
	s_add_i32 s64, 0, 0x1c000
	v_add_u32_e32 v142, s61, v248
	v_add_u32_e32 v182, s64, v248
	ds_read_b128 v[130:133], v142
	ds_read_b128 v[134:137], v142 offset:1024
	ds_read_b128 v[138:141], v142 offset:2048
	ds_read_b128 v[142:145], v142 offset:3072
	ds_read_b128 v[158:161], v182
	ds_read_b128 v[174:177], v182 offset:1024
	ds_read_b128 v[178:181], v182 offset:2048
	ds_read_b128 v[182:185], v182 offset:3072
	s_add_u32 s94, vcc_lo, 0x80000
	s_addc_u32 s95, vcc_hi, 0
	s_mov_b32 m0, s85
	s_nop 0
	global_load_lds_dwordx4 v[222:223], off
	s_mov_b32 m0, s86
	s_nop 0
	global_load_lds_dwordx4 v[224:225], off
	s_mov_b32 m0, s87
	v_lshl_add_u64 v[226:227], s[94:95], 0, v[146:147]
	ds_read_b128 v[186:189], v251 offset:32768
	ds_read_b128 v[190:193], v251 offset:33792
	ds_read_b128 v[194:197], v251 offset:34816
	ds_read_b128 v[198:201], v251 offset:35840
	ds_read_b128 v[202:205], v251 offset:36864
	ds_read_b128 v[206:209], v251 offset:37888
	ds_read_b128 v[210:213], v251 offset:38912
	ds_read_b128 v[214:217], v251 offset:39936
	global_load_lds_dwordx4 v[226:227], off
	v_lshl_add_u64 v[226:227], s[94:95], 0, v[148:149]
	s_mov_b32 m0, s88
	s_nop 0
	global_load_lds_dwordx4 v[226:227], off
	s_nop 0
	s_waitcnt vmcnt(8)
	s_waitcnt lgkmcnt(0)
	s_barrier
; #define PG8_STAGE(bufoff, gbase, voff) do { _Pragma("unroll") for (int _i = 0; _i < 2; ++_i) \
;         __builtin_amdgcn_global_load_lds((const __attribute__((address_space(1))) unsigned*)((const char*)(gbase) + (voff)[_i]), (LAS unsigned*)(lds + (bufoff) + ldsw + _i * 8192), 16, 0, 0); } while (0)
; #define PG8_LDA(dst, b, h) do { _Pragma("unroll") for (int m = 0; m < 4; ++m) _Pragma("unroll") for (int k = 0; k < 2; ++k) dst[m][k] = *(const LAS bf16x8*)(lds + PG8_SA(b, h) + aoff + m * 2048 + k * 1024); } while (0)
; #define PG8_MMA(ai, bj, At, Bt) do { __builtin_amdgcn_s_setprio(1); _Pragma("unroll") for (int m = 0; m < 4; ++m) _Pragma("unroll") for (int n = 0; n < 2; ++n) _Pragma("unroll") for (int k = 0; k < 2; ++k) \
;         acc[ai][bj][m][n] = __builtin_amdgcn_mfma_f32_16x16x32_bf16(Bt[n][k], At[m][k], acc[ai][bj][m][n], 0, 0, 0); __builtin_amdgcn_s_setprio(0); } while (0)
; #define PG8_WAIT_V(n) asm volatile("s_waitcnt vmcnt(" #n ")" ::: "memory")
; #define PG8_WAIT_L(n) asm volatile("s_waitcnt lgkmcnt(" #n ")" ::: "memory")
; #define PG8_BAR __builtin_amdgcn_s_barrier()
; #define PG8_SCHED __builtin_amdgcn_sched_barrier(0)
; template <class Epi, class SchedT, bool ALIGN_EPI, bool SP2>
; __device__ __forceinline__ void gemm_phase(LAS unsigned char* lds, const int ldk, const int nt, const SchedT& S, const Epi& E) {
;     ...
;             PG8_WAIT_V(8); PG8_WAIT_L(0); PG8_BAR; PG8_MMA(0, 0, At, B0); PG8_MMA(0, 1, At, B1); PG8_BAR; PG8_SCHED;
;             PG8_LDA(At, 1, 1); PG8_STAGE(PG8_SB(1, 0), b3, voffB); PG8_STAGE(PG8_SB(1, 1), b3 + hstepB, voffB); PG8_STAGE(PG8_SA(1, 0), a3, voffA);
;             PG8_WAIT_V(8); PG8_WAIT_L(0); PG8_BAR; PG8_MMA(1, 0, At, B0); PG8_MMA(1, 1, At, B1); PG8_BAR; PG8_SCHED;
;     ...
;         }
;         if constexpr (ALIGN_EPI) { if (wr == 0) PG8_BAR; }
	s_setprio 1
	s_waitcnt lgkmcnt(0)
	v_mfma_f32_16x16x32_bf16 v[126:129], v[130:133], v[186:189], v[126:129]
	v_mfma_f32_16x16x32_bf16 v[62:65], v[138:141], v[186:189], v[62:65]
	v_mfma_f32_16x16x32_bf16 v[118:121], v[130:133], v[194:197], v[118:121]
	v_mfma_f32_16x16x32_bf16 v[58:61], v[138:141], v[194:197], v[58:61]
	v_mfma_f32_16x16x32_bf16 v[110:113], v[130:133], v[202:205], v[110:113]
	v_mfma_f32_16x16x32_bf16 v[46:49], v[138:141], v[202:205], v[46:49]
	v_mfma_f32_16x16x32_bf16 v[106:109], v[130:133], v[210:213], v[106:109]
	v_mfma_f32_16x16x32_bf16 v[42:45], v[138:141], v[210:213], v[42:45]
	v_mfma_f32_16x16x32_bf16 v[126:129], v[134:137], v[190:193], v[126:129]
	v_mfma_f32_16x16x32_bf16 v[62:65], v[142:145], v[190:193], v[62:65]
	v_mfma_f32_16x16x32_bf16 v[118:121], v[134:137], v[198:201], v[118:121]
	v_mfma_f32_16x16x32_bf16 v[58:61], v[142:145], v[198:201], v[58:61]
	v_mfma_f32_16x16x32_bf16 v[110:113], v[134:137], v[206:209], v[110:113]
	v_mfma_f32_16x16x32_bf16 v[46:49], v[142:145], v[206:209], v[46:49]
	v_mfma_f32_16x16x32_bf16 v[106:109], v[134:137], v[214:217], v[106:109]
	v_mfma_f32_16x16x32_bf16 v[42:45], v[142:145], v[214:217], v[42:45]
	s_setprio 0
	s_setprio 1
	v_mfma_f32_16x16x32_bf16 v[122:125], v[158:161], v[186:189], v[122:125]
	v_mfma_f32_16x16x32_bf16 v[54:57], v[178:181], v[186:189], v[54:57]
	v_mfma_f32_16x16x32_bf16 v[114:117], v[158:161], v[194:197], v[114:117]
	v_mfma_f32_16x16x32_bf16 v[50:53], v[178:181], v[194:197], v[50:53]
	v_mfma_f32_16x16x32_bf16 v[102:105], v[158:161], v[202:205], v[102:105]
	v_mfma_f32_16x16x32_bf16 v[38:41], v[178:181], v[202:205], v[38:41]
	v_mfma_f32_16x16x32_bf16 v[98:101], v[158:161], v[210:213], v[98:101]
	v_mfma_f32_16x16x32_bf16 v[34:37], v[178:181], v[210:213], v[34:37]
	v_mfma_f32_16x16x32_bf16 v[122:125], v[174:177], v[190:193], v[122:125]
	v_mfma_f32_16x16x32_bf16 v[54:57], v[182:185], v[190:193], v[54:57]
	v_mfma_f32_16x16x32_bf16 v[114:117], v[174:177], v[198:201], v[114:117]
	v_mfma_f32_16x16x32_bf16 v[50:53], v[182:185], v[198:201], v[50:53]
	v_mfma_f32_16x16x32_bf16 v[102:105], v[174:177], v[206:209], v[102:105]
	v_mfma_f32_16x16x32_bf16 v[38:41], v[182:185], v[206:209], v[38:41]
	v_mfma_f32_16x16x32_bf16 v[98:101], v[174:177], v[214:217], v[98:101]
	v_mfma_f32_16x16x32_bf16 v[34:37], v[182:185], v[214:217], v[34:37]
	s_setprio 0
	s_barrier
	s_add_i32 s61, s61, s84
	v_lshl_add_u64 v[218:219], v[218:219], 0, s[24:25]
	s_mov_b32 m0, s61
	ds_read_b128 v[186:189], v251 offset:49152
	ds_read_b128 v[190:193], v251 offset:50176
	ds_read_b128 v[194:197], v251 offset:51200
	ds_read_b128 v[198:201], v251 offset:52224
	ds_read_b128 v[202:205], v251 offset:53248
	ds_read_b128 v[206:209], v251 offset:54272
	ds_read_b128 v[210:213], v251 offset:55296
	ds_read_b128 v[214:217], v251 offset:56320
	global_load_lds_dwordx4 v[218:219], off
	s_add_i32 m0, s61, 0x2000
	s_add_u32 s36, s36, 0x20080
	v_lshl_add_u64 v[218:219], v[220:221], 0, s[24:25]
	s_addc_u32 s37, s37, 0
	s_add_i32 s61, s64, s84
	global_load_lds_dwordx4 v[218:219], off
	v_lshl_add_u64 v[218:219], s[36:37], 0, v[0:1]
	s_mov_b32 m0, s61
	s_nop 0
	global_load_lds_dwordx4 v[218:219], off
	v_lshl_add_u64 v[218:219], s[36:37], 0, v[150:151]
	s_add_i32 m0, s61, 0x2000
	s_nop 0
	global_load_lds_dwordx4 v[218:219], off
	s_waitcnt vmcnt(6)
	s_waitcnt lgkmcnt(0)
	s_barrier
	s_setprio 1
	s_waitcnt lgkmcnt(0)
	v_mfma_f32_16x16x32_bf16 v[94:97], v[130:133], v[186:189], v[94:97]
	v_mfma_f32_16x16x32_bf16 v[30:33], v[138:141], v[186:189], v[30:33]
	v_mfma_f32_16x16x32_bf16 v[90:93], v[130:133], v[194:197], v[90:93]
	v_mfma_f32_16x16x32_bf16 v[26:29], v[138:141], v[194:197], v[26:29]
	v_mfma_f32_16x16x32_bf16 v[78:81], v[130:133], v[202:205], v[78:81]
	v_mfma_f32_16x16x32_bf16 v[14:17], v[138:141], v[202:205], v[14:17]
	v_mfma_f32_16x16x32_bf16 v[74:77], v[130:133], v[210:213], v[74:77]
	v_mfma_f32_16x16x32_bf16 v[10:13], v[138:141], v[210:213], v[10:13]
	v_mfma_f32_16x16x32_bf16 v[94:97], v[134:137], v[190:193], v[94:97]
	v_mfma_f32_16x16x32_bf16 v[30:33], v[142:145], v[190:193], v[30:33]
	v_mfma_f32_16x16x32_bf16 v[90:93], v[134:137], v[198:201], v[90:93]
	v_mfma_f32_16x16x32_bf16 v[26:29], v[142:145], v[198:201], v[26:29]
	v_mfma_f32_16x16x32_bf16 v[78:81], v[134:137], v[206:209], v[78:81]
	v_mfma_f32_16x16x32_bf16 v[14:17], v[142:145], v[206:209], v[14:17]
	v_mfma_f32_16x16x32_bf16 v[74:77], v[134:137], v[214:217], v[74:77]
	v_mfma_f32_16x16x32_bf16 v[10:13], v[142:145], v[214:217], v[10:13]
	s_setprio 0
	s_setprio 1
	v_mfma_f32_16x16x32_bf16 v[86:89], v[158:161], v[186:189], v[86:89]
	v_mfma_f32_16x16x32_bf16 v[22:25], v[178:181], v[186:189], v[22:25]
	v_mfma_f32_16x16x32_bf16 v[82:85], v[158:161], v[194:197], v[82:85]
	v_mfma_f32_16x16x32_bf16 v[18:21], v[178:181], v[194:197], v[18:21]
	v_mfma_f32_16x16x32_bf16 v[70:73], v[158:161], v[202:205], v[70:73]
	v_mfma_f32_16x16x32_bf16 v[6:9], v[178:181], v[202:205], v[6:9]
	v_mfma_f32_16x16x32_bf16 v[66:69], v[158:161], v[210:213], v[66:69]
	v_mfma_f32_16x16x32_bf16 v[2:5], v[178:181], v[210:213], v[2:5]
	v_mfma_f32_16x16x32_bf16 v[86:89], v[174:177], v[190:193], v[86:89]
	v_mfma_f32_16x16x32_bf16 v[22:25], v[182:185], v[190:193], v[22:25]
	v_mfma_f32_16x16x32_bf16 v[82:85], v[174:177], v[198:201], v[82:85]
	v_mfma_f32_16x16x32_bf16 v[18:21], v[182:185], v[198:201], v[18:21]
	v_mfma_f32_16x16x32_bf16 v[70:73], v[174:177], v[206:209], v[70:73]
	v_mfma_f32_16x16x32_bf16 v[6:9], v[182:185], v[206:209], v[6:9]
	v_mfma_f32_16x16x32_bf16 v[66:69], v[174:177], v[214:217], v[66:69]
	v_mfma_f32_16x16x32_bf16 v[2:5], v[182:185], v[214:217], v[2:5]
	s_setprio 0
	s_barrier
	s_add_i32 s59, s59, 2
	s_add_u32 s34, s34, 0x100
	s_addc_u32 s35, s35, 0
	s_add_u32 s13, s13, 0x100
	s_addc_u32 s17, s17, 0
	s_cmp_gt_u32 s59, 29
	s_cbranch_scc0 .LBB0_752
	s_and_b64 vcc, exec, s[56:57]
	s_cbranch_vccz .LBB0_755
	s_barrier

; #define PG8_STAGE(bufoff, gbase, voff) do { _Pragma("unroll") for (int _i = 0; _i < 2; ++_i) \
;         __builtin_amdgcn_global_load_lds((const __attribute__((address_space(1))) unsigned*)((const char*)(gbase) + (voff)[_i]), (LAS unsigned*)(lds + (bufoff) + ldsw + _i * 8192), 16, 0, 0); } while (0)
; #define PG8_LDA(dst, b, h) do { _Pragma("unroll") for (int m = 0; m < 4; ++m) _Pragma("unroll") for (int k = 0; k < 2; ++k) dst[m][k] = *(const LAS bf16x8*)(lds + PG8_SA(b, h) + aoff + m * 2048 + k * 1024); } while (0)
; #define PG8_LDB(dst, b, h) do { _Pragma("unroll") for (int n = 0; n < 2; ++n) _Pragma("unroll") for (int k = 0; k < 2; ++k) dst[n][k] = *(const LAS bf16x8*)(lds + PG8_SB(b, h) + boff + n * 2048 + k * 1024); } while (0)
; #define PG8_MMA(ai, bj, At, Bt) do { __builtin_amdgcn_s_setprio(1); _Pragma("unroll") for (int m = 0; m < 4; ++m) _Pragma("unroll") for (int n = 0; n < 2; ++n) _Pragma("unroll") for (int k = 0; k < 2; ++k) \
;         acc[ai][bj][m][n] = __builtin_amdgcn_mfma_f32_16x16x32_bf16(Bt[n][k], At[m][k], acc[ai][bj][m][n], 0, 0, 0); __builtin_amdgcn_s_setprio(0); } while (0)
; #define PG8_WAIT_V(n) asm volatile("s_waitcnt vmcnt(" #n ")" ::: "memory")
; #define PG8_WAIT_L(n) asm volatile("s_waitcnt lgkmcnt(" #n ")" ::: "memory")
; #define PG8_BAR __builtin_amdgcn_s_barrier()
; template <class Epi, class SchedT, bool ALIGN_EPI, bool SP2>
; __device__ __forceinline__ void gemm_phase(LAS unsigned char* lds, const int ldk, const int nt, const SchedT& S, const Epi& E) {
;     ...
;             const bool last = (t == nt - 2);
;             const char* a1 = cA + (size_t)(t + 1) * kstep;
;             const char* a2 = last ? nA : cA + (size_t)(t + 2) * kstep; const char* b2 = last ? nB : cB + (size_t)(t + 2) * kstep;
;             const char* a3 = a2 + kstep; const char* b3 = b2 + kstep;
;             if constexpr (SP2) {
;             PG8_LDB(B0, 0, 0); PG8_LDB(B1, 0, 1); PG8_SCHED; PG8_LDA(At, 0, 0); PG8_STAGE(PG8_SA(1, 1), a1 + hstep, voffA);
;             PG8_WAIT_V(8); PG8_WAIT_L(0); PG8_BAR; PG8_MMA(0, 0, At, B0); PG8_MMA(0, 1, At, B1); PG8_BAR; PG8_SCHED;
;             PG8_LDA(At, 0, 1); PG8_STAGE(PG8_SB(0, 0), b2, voffB); PG8_STAGE(PG8_SB(0, 1), b2 + hstepB, voffB); PG8_STAGE(PG8_SA(0, 0), a2, voffA);
;             PG8_WAIT_V(8); PG8_WAIT_L(0); PG8_BAR; PG8_MMA(1, 0, At, B0); PG8_MMA(1, 1, At, B1); PG8_BAR; PG8_SCHED;
.LBB0_948:
	s_add_u32 s16, s12, 0x100
	s_addc_u32 s17, s13, 0
	s_add_i32 s64, 0, 0x10000
	s_cmpk_eq_i32 s83, 0x52
	s_cselect_b32 s47, s1, s17
	s_cselect_b32 s46, s0, s16
	v_add_u32_e32 v144, s64, v147
	s_cselect_b32 s45, s43, s82
	s_cselect_b32 s44, s42, s81
	s_add_i32 s65, 0, 0x14000
	ds_read_b128 v[140:143], v144
	ds_read_b128 v[150:153], v144 offset:1024
	ds_read_b128 v[154:157], v144 offset:2048
	ds_read_b128 v[158:161], v144 offset:3072
	v_add_u32_e32 v144, s65, v147
	ds_read_b128 v[174:177], v144
	ds_read_b128 v[178:181], v144 offset:1024
	ds_read_b128 v[182:185], v144 offset:2048
	ds_read_b128 v[186:189], v144 offset:3072
	v_lshl_add_u64 v[144:145], s[12:13], 0, v[136:137]
	s_add_i32 m0, s53, 0xc000
	ds_read_b128 v[190:193], v149
	ds_read_b128 v[194:197], v149 offset:1024
	ds_read_b128 v[198:201], v149 offset:2048
	ds_read_b128 v[202:205], v149 offset:3072
	ds_read_b128 v[206:209], v149 offset:4096
	ds_read_b128 v[210:213], v149 offset:5120
	ds_read_b128 v[214:217], v149 offset:6144
	ds_read_b128 v[218:221], v149 offset:7168
	global_load_lds_dwordx4 v[144:145], off
	v_lshl_add_u64 v[144:145], s[12:13], 0, v[138:139]
	s_add_i32 m0, s53, 0xe000
	s_nop 0
	global_load_lds_dwordx4 v[144:145], off
	s_nop 0
	s_nop 0
	s_nop 0
	s_nop 0
	s_nop 0
	s_waitcnt vmcnt(8)
	s_waitcnt lgkmcnt(0)
	s_barrier
	s_setprio 1
	s_waitcnt lgkmcnt(0)
	v_mfma_f32_16x16x32_bf16 v[126:129], v[140:143], v[190:193], v[126:129]
	v_mfma_f32_16x16x32_bf16 v[122:125], v[154:157], v[190:193], v[122:125]
	v_mfma_f32_16x16x32_bf16 v[110:113], v[140:143], v[198:201], v[110:113]
	v_mfma_f32_16x16x32_bf16 v[106:109], v[154:157], v[198:201], v[106:109]
	v_mfma_f32_16x16x32_bf16 v[94:97], v[140:143], v[206:209], v[94:97]
	v_mfma_f32_16x16x32_bf16 v[90:93], v[154:157], v[206:209], v[90:93]
	v_mfma_f32_16x16x32_bf16 v[78:81], v[140:143], v[214:217], v[78:81]
	v_mfma_f32_16x16x32_bf16 v[74:77], v[154:157], v[214:217], v[74:77]
	v_mfma_f32_16x16x32_bf16 v[126:129], v[150:153], v[194:197], v[126:129]
	v_mfma_f32_16x16x32_bf16 v[122:125], v[158:161], v[194:197], v[122:125]
	v_mfma_f32_16x16x32_bf16 v[110:113], v[150:153], v[202:205], v[110:113]
	v_mfma_f32_16x16x32_bf16 v[106:109], v[158:161], v[202:205], v[106:109]
	v_mfma_f32_16x16x32_bf16 v[94:97], v[150:153], v[210:213], v[94:97]
	v_mfma_f32_16x16x32_bf16 v[90:93], v[158:161], v[210:213], v[90:93]
	v_mfma_f32_16x16x32_bf16 v[78:81], v[150:153], v[218:221], v[78:81]
	v_mfma_f32_16x16x32_bf16 v[74:77], v[158:161], v[218:221], v[74:77]
	s_setprio 0
	s_setprio 1
	v_mfma_f32_16x16x32_bf16 v[118:121], v[174:177], v[190:193], v[118:121]
	v_mfma_f32_16x16x32_bf16 v[114:117], v[182:185], v[190:193], v[114:117]
	v_mfma_f32_16x16x32_bf16 v[102:105], v[174:177], v[198:201], v[102:105]
	v_mfma_f32_16x16x32_bf16 v[98:101], v[182:185], v[198:201], v[98:101]
	v_mfma_f32_16x16x32_bf16 v[86:89], v[174:177], v[206:209], v[86:89]
	v_mfma_f32_16x16x32_bf16 v[82:85], v[182:185], v[206:209], v[82:85]
	v_mfma_f32_16x16x32_bf16 v[70:73], v[174:177], v[214:217], v[70:73]
	v_mfma_f32_16x16x32_bf16 v[66:69], v[182:185], v[214:217], v[66:69]
	v_mfma_f32_16x16x32_bf16 v[118:121], v[178:181], v[194:197], v[118:121]
	v_mfma_f32_16x16x32_bf16 v[114:117], v[186:189], v[194:197], v[114:117]
	v_mfma_f32_16x16x32_bf16 v[102:105], v[178:181], v[202:205], v[102:105]
	v_mfma_f32_16x16x32_bf16 v[98:101], v[186:189], v[202:205], v[98:101]
	v_mfma_f32_16x16x32_bf16 v[86:89], v[178:181], v[210:213], v[86:89]
	v_mfma_f32_16x16x32_bf16 v[82:85], v[186:189], v[210:213], v[82:85]
	v_mfma_f32_16x16x32_bf16 v[70:73], v[178:181], v[218:221], v[70:73]
	v_mfma_f32_16x16x32_bf16 v[66:69], v[186:189], v[218:221], v[66:69]
	s_setprio 0
	s_barrier
	s_add_i32 s12, s64, s52
	v_lshl_add_u64 v[144:145], s[44:45], 0, v[0:1]
	s_mov_b32 m0, s12
	ds_read_b128 v[190:193], v149 offset:16384
	ds_read_b128 v[194:197], v149 offset:17408
	ds_read_b128 v[198:201], v149 offset:18432
	ds_read_b128 v[202:205], v149 offset:19456
	ds_read_b128 v[206:209], v149 offset:20480
	ds_read_b128 v[210:213], v149 offset:21504
	ds_read_b128 v[214:217], v149 offset:22528
	ds_read_b128 v[218:221], v149 offset:23552
	global_load_lds_dwordx4 v[144:145], off
	s_add_i32 m0, s12, 0x2000
	s_add_u32 s12, s44, 0x56000
	v_lshl_add_u64 v[222:223], s[44:45], 0, v[134:135]
	s_addc_u32 s13, s45, 0
	s_add_i32 s64, s65, s52
	global_load_lds_dwordx4 v[222:223], off
	v_lshl_add_u64 v[224:225], s[12:13], 0, v[0:1]
	s_mov_b32 m0, s64
	v_lshl_add_u64 v[226:227], s[46:47], 0, v[132:133]
	global_load_lds_dwordx4 v[224:225], off
	v_lshl_add_u64 v[224:225], s[12:13], 0, v[134:135]
	s_add_i32 m0, s64, 0x2000
	s_nop 0
	global_load_lds_dwordx4 v[224:225], off
	v_lshl_add_u64 v[224:225], s[46:47], 0, v[130:131]
	s_mov_b32 m0, s53
	s_nop 0
	global_load_lds_dwordx4 v[224:225], off
	s_mov_b32 m0, s54
	s_nop 0
	global_load_lds_dwordx4 v[226:227], off
	s_nop 0
	s_waitcnt vmcnt(8)
	s_waitcnt lgkmcnt(0)
	s_barrier
; #define PG8_STAGE(bufoff, gbase, voff) do { _Pragma("unroll") for (int _i = 0; _i < 2; ++_i) \
;         __builtin_amdgcn_global_load_lds((const __attribute__((address_space(1))) unsigned*)((const char*)(gbase) + (voff)[_i]), (LAS unsigned*)(lds + (bufoff) + ldsw + _i * 8192), 16, 0, 0); } while (0)
; #define PG8_LDA(dst, b, h) do { _Pragma("unroll") for (int m = 0; m < 4; ++m) _Pragma("unroll") for (int k = 0; k < 2; ++k) dst[m][k] = *(const LAS bf16x8*)(lds + PG8_SA(b, h) + aoff + m * 2048 + k * 1024); } while (0)
; #define PG8_LDB(dst, b, h) do { _Pragma("unroll") for (int n = 0; n < 2; ++n) _Pragma("unroll") for (int k = 0; k < 2; ++k) dst[n][k] = *(const LAS bf16x8*)(lds + PG8_SB(b, h) + boff + n * 2048 + k * 1024); } while (0)
; #define PG8_MMA(ai, bj, At, Bt) do { __builtin_amdgcn_s_setprio(1); _Pragma("unroll") for (int m = 0; m < 4; ++m) _Pragma("unroll") for (int n = 0; n < 2; ++n) _Pragma("unroll") for (int k = 0; k < 2; ++k) \
;         acc[ai][bj][m][n] = __builtin_amdgcn_mfma_f32_16x16x32_bf16(Bt[n][k], At[m][k], acc[ai][bj][m][n], 0, 0, 0); __builtin_amdgcn_s_setprio(0); } while (0)
; #define PG8_WAIT_V(n) asm volatile("s_waitcnt vmcnt(" #n ")" ::: "memory")
; #define PG8_WAIT_L(n) asm volatile("s_waitcnt lgkmcnt(" #n ")" ::: "memory")
; #define PG8_BAR __builtin_amdgcn_s_barrier()
; #define PG8_SCHED __builtin_amdgcn_sched_barrier(0)
; template <class Epi, class SchedT, bool ALIGN_EPI, bool SP2>
; __device__ __forceinline__ void gemm_phase(LAS unsigned char* lds, const int ldk, const int nt, const SchedT& S, const Epi& E) {
;     ...
;             PG8_WAIT_V(8); PG8_WAIT_L(0); PG8_BAR; PG8_MMA(1, 0, At, B0); PG8_MMA(1, 1, At, B1); PG8_BAR; PG8_SCHED;
;             PG8_LDB(B0, 1, 0); PG8_LDB(B1, 1, 1); PG8_SCHED; PG8_LDA(At, 1, 0); PG8_STAGE(PG8_SA(0, 1), a2 + hstep, voffA);
;             PG8_WAIT_V(8); PG8_WAIT_L(0); PG8_BAR; PG8_MMA(0, 0, At, B0); PG8_MMA(0, 1, At, B1); PG8_BAR; PG8_SCHED;
	s_setprio 1
	s_waitcnt lgkmcnt(0)
	v_mfma_f32_16x16x32_bf16 v[62:65], v[140:143], v[190:193], v[62:65]
	v_mfma_f32_16x16x32_bf16 v[58:61], v[154:157], v[190:193], v[58:61]
	v_mfma_f32_16x16x32_bf16 v[46:49], v[140:143], v[198:201], v[46:49]
	v_mfma_f32_16x16x32_bf16 v[42:45], v[154:157], v[198:201], v[42:45]
	v_mfma_f32_16x16x32_bf16 v[30:33], v[140:143], v[206:209], v[30:33]
	v_mfma_f32_16x16x32_bf16 v[26:29], v[154:157], v[206:209], v[26:29]
	v_mfma_f32_16x16x32_bf16 v[14:17], v[140:143], v[214:217], v[14:17]
	v_mfma_f32_16x16x32_bf16 v[10:13], v[154:157], v[214:217], v[10:13]
	v_mfma_f32_16x16x32_bf16 v[62:65], v[150:153], v[194:197], v[62:65]
	v_mfma_f32_16x16x32_bf16 v[58:61], v[158:161], v[194:197], v[58:61]
	v_mfma_f32_16x16x32_bf16 v[46:49], v[150:153], v[202:205], v[46:49]
	v_mfma_f32_16x16x32_bf16 v[42:45], v[158:161], v[202:205], v[42:45]
	v_mfma_f32_16x16x32_bf16 v[30:33], v[150:153], v[210:213], v[30:33]
	v_mfma_f32_16x16x32_bf16 v[26:29], v[158:161], v[210:213], v[26:29]
	v_mfma_f32_16x16x32_bf16 v[14:17], v[150:153], v[218:221], v[14:17]
	v_mfma_f32_16x16x32_bf16 v[10:13], v[158:161], v[218:221], v[10:13]
	s_setprio 0
	s_setprio 1
	v_mfma_f32_16x16x32_bf16 v[54:57], v[174:177], v[190:193], v[54:57]
	v_mfma_f32_16x16x32_bf16 v[50:53], v[182:185], v[190:193], v[50:53]
	v_mfma_f32_16x16x32_bf16 v[38:41], v[174:177], v[198:201], v[38:41]
	v_mfma_f32_16x16x32_bf16 v[34:37], v[182:185], v[198:201], v[34:37]
	v_mfma_f32_16x16x32_bf16 v[22:25], v[174:177], v[206:209], v[22:25]
	v_mfma_f32_16x16x32_bf16 v[18:21], v[182:185], v[206:209], v[18:21]
	v_mfma_f32_16x16x32_bf16 v[6:9], v[174:177], v[214:217], v[6:9]
	v_mfma_f32_16x16x32_bf16 v[2:5], v[182:185], v[214:217], v[2:5]
	v_mfma_f32_16x16x32_bf16 v[54:57], v[178:181], v[194:197], v[54:57]
	v_mfma_f32_16x16x32_bf16 v[50:53], v[186:189], v[194:197], v[50:53]
	v_mfma_f32_16x16x32_bf16 v[38:41], v[178:181], v[202:205], v[38:41]
	v_mfma_f32_16x16x32_bf16 v[34:37], v[186:189], v[202:205], v[34:37]
	v_mfma_f32_16x16x32_bf16 v[22:25], v[178:181], v[210:213], v[22:25]
	v_mfma_f32_16x16x32_bf16 v[18:21], v[186:189], v[210:213], v[18:21]
	v_mfma_f32_16x16x32_bf16 v[6:9], v[178:181], v[218:221], v[6:9]
	v_mfma_f32_16x16x32_bf16 v[2:5], v[186:189], v[218:221], v[2:5]
	s_setprio 0
	s_barrier
	s_add_i32 s64, 0, 0x18000
	s_add_i32 s65, 0, 0x1c000
	v_add_u32_e32 v158, s64, v147
	v_add_u32_e32 v186, s65, v147
	ds_read_b128 v[140:143], v158
	ds_read_b128 v[150:153], v158 offset:1024
	ds_read_b128 v[154:157], v158 offset:2048
	ds_read_b128 v[158:161], v158 offset:3072
	ds_read_b128 v[174:177], v186
	ds_read_b128 v[178:181], v186 offset:1024
	ds_read_b128 v[182:185], v186 offset:2048
	ds_read_b128 v[186:189], v186 offset:3072
	s_add_u32 s12, s46, 0x158000
	s_addc_u32 s13, s47, 0
	s_mov_b32 m0, s55
	v_lshl_add_u64 v[228:229], s[12:13], 0, v[130:131]
	ds_read_b128 v[190:193], v149 offset:32768
	ds_read_b128 v[194:197], v149 offset:33792
	ds_read_b128 v[198:201], v149 offset:34816
	ds_read_b128 v[202:205], v149 offset:35840
	ds_read_b128 v[206:209], v149 offset:36864
	ds_read_b128 v[210:213], v149 offset:37888
	ds_read_b128 v[214:217], v149 offset:38912
	ds_read_b128 v[218:221], v149 offset:39936
	global_load_lds_dwordx4 v[228:229], off
	v_lshl_add_u64 v[228:229], s[12:13], 0, v[132:133]
	s_mov_b32 m0, s56
	s_nop 0
	global_load_lds_dwordx4 v[228:229], off
	s_nop 0
	s_waitcnt vmcnt(8)
	s_waitcnt lgkmcnt(0)
	s_barrier
	s_setprio 1
	s_waitcnt lgkmcnt(0)
	v_mfma_f32_16x16x32_bf16 v[126:129], v[140:143], v[190:193], v[126:129]
	v_mfma_f32_16x16x32_bf16 v[122:125], v[154:157], v[190:193], v[122:125]
	v_mfma_f32_16x16x32_bf16 v[110:113], v[140:143], v[198:201], v[110:113]
	v_mfma_f32_16x16x32_bf16 v[106:109], v[154:157], v[198:201], v[106:109]
	v_mfma_f32_16x16x32_bf16 v[94:97], v[140:143], v[206:209], v[94:97]
	v_mfma_f32_16x16x32_bf16 v[90:93], v[154:157], v[206:209], v[90:93]
	v_mfma_f32_16x16x32_bf16 v[78:81], v[140:143], v[214:217], v[78:81]
	v_mfma_f32_16x16x32_bf16 v[74:77], v[154:157], v[214:217], v[74:77]
	v_mfma_f32_16x16x32_bf16 v[126:129], v[150:153], v[194:197], v[126:129]
	v_mfma_f32_16x16x32_bf16 v[122:125], v[158:161], v[194:197], v[122:125]
	v_mfma_f32_16x16x32_bf16 v[110:113], v[150:153], v[202:205], v[110:113]
	v_mfma_f32_16x16x32_bf16 v[106:109], v[158:161], v[202:205], v[106:109]
	v_mfma_f32_16x16x32_bf16 v[94:97], v[150:153], v[210:213], v[94:97]
	v_mfma_f32_16x16x32_bf16 v[90:93], v[158:161], v[210:213], v[90:93]
	v_mfma_f32_16x16x32_bf16 v[78:81], v[150:153], v[218:221], v[78:81]
	v_mfma_f32_16x16x32_bf16 v[74:77], v[158:161], v[218:221], v[74:77]
	s_setprio 0
	s_setprio 1
	v_mfma_f32_16x16x32_bf16 v[118:121], v[174:177], v[190:193], v[118:121]
	v_mfma_f32_16x16x32_bf16 v[114:117], v[182:185], v[190:193], v[114:117]
	v_mfma_f32_16x16x32_bf16 v[102:105], v[174:177], v[198:201], v[102:105]
	v_mfma_f32_16x16x32_bf16 v[98:101], v[182:185], v[198:201], v[98:101]
	v_mfma_f32_16x16x32_bf16 v[86:89], v[174:177], v[206:209], v[86:89]
	v_mfma_f32_16x16x32_bf16 v[82:85], v[182:185], v[206:209], v[82:85]
	v_mfma_f32_16x16x32_bf16 v[70:73], v[174:177], v[214:217], v[70:73]
	v_mfma_f32_16x16x32_bf16 v[66:69], v[182:185], v[214:217], v[66:69]
	v_mfma_f32_16x16x32_bf16 v[118:121], v[178:181], v[194:197], v[118:121]
	v_mfma_f32_16x16x32_bf16 v[114:117], v[186:189], v[194:197], v[114:117]
	v_mfma_f32_16x16x32_bf16 v[102:105], v[178:181], v[202:205], v[102:105]
	v_mfma_f32_16x16x32_bf16 v[98:101], v[186:189], v[202:205], v[98:101]
	v_mfma_f32_16x16x32_bf16 v[86:89], v[178:181], v[210:213], v[86:89]
	v_mfma_f32_16x16x32_bf16 v[82:85], v[186:189], v[210:213], v[82:85]
	v_mfma_f32_16x16x32_bf16 v[70:73], v[178:181], v[218:221], v[70:73]
	v_mfma_f32_16x16x32_bf16 v[66:69], v[186:189], v[218:221], v[66:69]
	s_setprio 0
	s_barrier
; #define PG8_STAGE(bufoff, gbase, voff) do { _Pragma("unroll") for (int _i = 0; _i < 2; ++_i) \
;         __builtin_amdgcn_global_load_lds((const __attribute__((address_space(1))) unsigned*)((const char*)(gbase) + (voff)[_i]), (LAS unsigned*)(lds + (bufoff) + ldsw + _i * 8192), 16, 0, 0); } while (0)
; #define PG8_LDA(dst, b, h) do { _Pragma("unroll") for (int m = 0; m < 4; ++m) _Pragma("unroll") for (int k = 0; k < 2; ++k) dst[m][k] = *(const LAS bf16x8*)(lds + PG8_SA(b, h) + aoff + m * 2048 + k * 1024); } while (0)
; #define PG8_MMA(ai, bj, At, Bt) do { __builtin_amdgcn_s_setprio(1); _Pragma("unroll") for (int m = 0; m < 4; ++m) _Pragma("unroll") for (int n = 0; n < 2; ++n) _Pragma("unroll") for (int k = 0; k < 2; ++k) \
;         acc[ai][bj][m][n] = __builtin_amdgcn_mfma_f32_16x16x32_bf16(Bt[n][k], At[m][k], acc[ai][bj][m][n], 0, 0, 0); __builtin_amdgcn_s_setprio(0); } while (0)
; #define PG8_WAIT_V(n) asm volatile("s_waitcnt vmcnt(" #n ")" ::: "memory")
; #define PG8_WAIT_L(n) asm volatile("s_waitcnt lgkmcnt(" #n ")" ::: "memory")
; #define PG8_BAR __builtin_amdgcn_s_barrier()
; #define PG8_SCHED __builtin_amdgcn_sched_barrier(0)
; template <class Epi, class SchedT, bool ALIGN_EPI, bool SP2>
; __device__ __forceinline__ void gemm_phase(LAS unsigned char* lds, const int ldk, const int nt, const SchedT& S, const Epi& E) {
;     ...
;             PG8_LDA(At, 1, 1); PG8_STAGE(PG8_SB(1, 0), b3, voffB); PG8_STAGE(PG8_SB(1, 1), b3 + hstepB, voffB); PG8_STAGE(PG8_SA(1, 0), a3, voffA);
;             PG8_WAIT_V(8); PG8_WAIT_L(0); PG8_BAR; PG8_MMA(1, 0, At, B0); PG8_MMA(1, 1, At, B1); PG8_BAR; PG8_SCHED;
;     __device__ __forceinline__ void operator()(f32x4 (&acc)[2][2][4][2], const Unit& u, int wr, int wc, int fr, int fq) const {
;         const int row0 = u.pm * BM + wr * 64 + fr, col0 = u.pn * BM + wc * 64 + 8 * fq;
; #pragma unroll
;         for (int ai = 0; ai < 2; ++ai)
; #pragma unroll
;             for (int m = 0; m < 4; ++m) {
;                 const int row = row0 + ai * HALF + m * 16; float sq = 0.f;
; #pragma unroll
;                 for (int bj = 0; bj < 2; ++bj) {
;                     const size_t off = (size_t)row * D + col0 + bj * 32;
;                     const u32x4 xw = *(const u32x4*)(xin + off);
	s_add_i32 s12, s64, s52
	v_lshl_add_u64 v[144:145], v[144:145], 0, s[24:25]
	s_mov_b32 m0, s12
	ds_read_b128 v[190:193], v149 offset:49152
	ds_read_b128 v[194:197], v149 offset:50176
	ds_read_b128 v[198:201], v149 offset:51200
	ds_read_b128 v[202:205], v149 offset:52224
	ds_read_b128 v[206:209], v149 offset:53248
	ds_read_b128 v[210:213], v149 offset:54272
	ds_read_b128 v[214:217], v149 offset:55296
	ds_read_b128 v[218:221], v149 offset:56320
	global_load_lds_dwordx4 v[144:145], off
	s_add_i32 m0, s12, 0x2000
	s_add_u32 s12, s44, 0x56080
	v_lshl_add_u64 v[144:145], v[222:223], 0, s[24:25]
	s_addc_u32 s13, s45, 0
	s_add_i32 s44, s65, s52
	global_load_lds_dwordx4 v[144:145], off
	v_lshl_add_u64 v[144:145], s[12:13], 0, v[0:1]
	s_mov_b32 m0, s44
	s_nop 0
	global_load_lds_dwordx4 v[144:145], off
	v_lshl_add_u64 v[144:145], s[12:13], 0, v[134:135]
	s_add_i32 m0, s44, 0x2000
	s_nop 0
	global_load_lds_dwordx4 v[144:145], off
	v_lshl_add_u64 v[144:145], v[224:225], 0, s[24:25]
	s_mov_b32 m0, s58
	s_nop 0
	global_load_lds_dwordx4 v[144:145], off
	v_lshl_add_u64 v[144:145], v[226:227], 0, s[24:25]
	s_mov_b32 m0, s59
	s_nop 0
	global_load_lds_dwordx4 v[144:145], off
	s_waitcnt vmcnt(8)
	s_waitcnt lgkmcnt(0)
	s_barrier
	s_setprio 1
	s_waitcnt lgkmcnt(0)
	v_mfma_f32_16x16x32_bf16 v[62:65], v[140:143], v[190:193], v[62:65]
	v_mfma_f32_16x16x32_bf16 v[58:61], v[154:157], v[190:193], v[58:61]
	v_mfma_f32_16x16x32_bf16 v[46:49], v[140:143], v[198:201], v[46:49]
	v_mfma_f32_16x16x32_bf16 v[42:45], v[154:157], v[198:201], v[42:45]
	v_mfma_f32_16x16x32_bf16 v[30:33], v[140:143], v[206:209], v[30:33]
	v_mfma_f32_16x16x32_bf16 v[26:29], v[154:157], v[206:209], v[26:29]
	v_mfma_f32_16x16x32_bf16 v[14:17], v[140:143], v[214:217], v[14:17]
	v_mfma_f32_16x16x32_bf16 v[10:13], v[154:157], v[214:217], v[10:13]
	v_mfma_f32_16x16x32_bf16 v[62:65], v[150:153], v[194:197], v[62:65]
	v_mfma_f32_16x16x32_bf16 v[58:61], v[158:161], v[194:197], v[58:61]
	v_mfma_f32_16x16x32_bf16 v[46:49], v[150:153], v[202:205], v[46:49]
	v_mfma_f32_16x16x32_bf16 v[42:45], v[158:161], v[202:205], v[42:45]
	v_mfma_f32_16x16x32_bf16 v[30:33], v[150:153], v[210:213], v[30:33]
	v_mfma_f32_16x16x32_bf16 v[26:29], v[158:161], v[210:213], v[26:29]
	v_mfma_f32_16x16x32_bf16 v[14:17], v[150:153], v[218:221], v[14:17]
	v_mfma_f32_16x16x32_bf16 v[10:13], v[158:161], v[218:221], v[10:13]
	s_setprio 0
	s_setprio 1
	v_mfma_f32_16x16x32_bf16 v[54:57], v[174:177], v[190:193], v[54:57]
	v_mfma_f32_16x16x32_bf16 v[50:53], v[182:185], v[190:193], v[50:53]
	v_mfma_f32_16x16x32_bf16 v[38:41], v[174:177], v[198:201], v[38:41]
	v_mfma_f32_16x16x32_bf16 v[34:37], v[182:185], v[198:201], v[34:37]
	v_mfma_f32_16x16x32_bf16 v[22:25], v[174:177], v[206:209], v[22:25]
	v_mfma_f32_16x16x32_bf16 v[18:21], v[182:185], v[206:209], v[18:21]
	v_mfma_f32_16x16x32_bf16 v[6:9], v[174:177], v[214:217], v[6:9]
	v_mfma_f32_16x16x32_bf16 v[2:5], v[182:185], v[214:217], v[2:5]
	v_mfma_f32_16x16x32_bf16 v[54:57], v[178:181], v[194:197], v[54:57]
	v_mfma_f32_16x16x32_bf16 v[50:53], v[186:189], v[194:197], v[50:53]
	v_mfma_f32_16x16x32_bf16 v[38:41], v[178:181], v[202:205], v[38:41]
	v_mfma_f32_16x16x32_bf16 v[34:37], v[186:189], v[202:205], v[34:37]
	v_mfma_f32_16x16x32_bf16 v[22:25], v[178:181], v[210:213], v[22:25]
	v_mfma_f32_16x16x32_bf16 v[18:21], v[186:189], v[210:213], v[18:21]
	v_mfma_f32_16x16x32_bf16 v[6:9], v[178:181], v[218:221], v[6:9]
	v_mfma_f32_16x16x32_bf16 v[2:5], v[186:189], v[218:221], v[2:5]
	s_setprio 0
	s_barrier
	s_add_i32 s83, s83, 2
	s_add_u32 s81, s81, 0x100
	s_addc_u32 s82, s82, 0
	s_cmpk_gt_u32 s83, 0x53
	s_mov_b64 s[12:13], s[16:17]
	s_cbranch_scc0 .LBB0_948
	v_lshl_add_u32 v142, s63, 8, v146
	v_lshl_or_b32 v140, s22, 8, v148
	v_lshlrev_b32_e32 v141, 12, v142
	v_lshl_add_u32 v150, v140, 1, v141
	v_add_u32_e32 v151, 0x10000, v150
	v_add_u32_e32 v152, 0x20000, v150
	v_add_u32_e32 v153, 0x30000, v150
	v_add_u32_e32 v154, 0x80000, v150
	v_add_u32_e32 v155, 0x90000, v150
	v_add_u32_e32 v156, 0xa0000, v150
	v_add_u32_e32 v157, 0xb0000, v150
	global_load_dwordx4 v[174:177], v150, s[20:21]
	global_load_dwordx4 v[178:181], v150, s[20:21] offset:64
	global_load_dwordx4 v[182:185], v151, s[20:21]
	global_load_dwordx4 v[186:189], v151, s[20:21] offset:64
	global_load_dwordx4 v[190:193], v152, s[20:21]
	global_load_dwordx4 v[194:197], v152, s[20:21] offset:64
	global_load_dwordx4 v[198:201], v153, s[20:21]
	global_load_dwordx4 v[202:205], v153, s[20:21] offset:64
	global_load_dwordx4 v[206:209], v154, s[20:21]
	global_load_dwordx4 v[210:213], v154, s[20:21] offset:64
	global_load_dwordx4 v[214:217], v155, s[20:21]
	global_load_dwordx4 v[218:221], v155, s[20:21] offset:64
	global_load_dwordx4 v[222:225], v156, s[20:21]
	global_load_dwordx4 v[226:229], v156, s[20:21] offset:64
	global_load_dwordx4 v[230:233], v157, s[20:21]
	global_load_dwordx4 v[234:237], v157, s[20:21] offset:64
	s_lshl_b32 s44, s22, 4
	s_lshl_b32 s45, s57, 2
	s_add_i32 s44, s44, s45
	v_lshl_add_u32 v158, v142, 7, s44
	v_add_u32_e32 v159, 0x1000, v158
	v_add_u32_e32 v160, 0x4000, v158
	v_add_u32_e32 v161, 0x5000, v158
	v_xor_b32_e32 v239, 16, v241
	v_xor_b32_e32 v252, 32, v241
	v_lshlrev_b32_e32 v239, 2, v239
	v_lshlrev_b32_e32 v252, 2, v252
	s_and_b64 vcc, exec, s[40:41]
	s_cbranch_vccz .LBB0_951
	s_barrier
